# per-pair recurrence scalars streamed through SMEM into an SGPR ring instead of LDS broadcast loads (8 fewer LDS dwords per pair per lane)
# speedup vs baseline: 1.0338x; 1.0029x over previous
.LBB0_822:
	s_or_b64 exec, exec, s[0:1]
	s_cmp_gt_u32 s38, 47
	s_cselect_b32 s0, 0x4000000, 0
	s_add_u32 s22, s78, s0
	s_addc_u32 s23, s79, 0
	s_lshl_b32 s0, s14, 7
	s_add_i32 s1, s0, 0xfffffd00
	s_cmp_lt_u32 s38, 48
	s_cselect_b32 s14, s0, s1
	s_lshl_b64 s[0:1], s[14:15], 1
	s_add_u32 s0, s22, s0
	s_addc_u32 s1, s23, s1
	s_lshl_b32 s14, s72, 4
	s_and_b32 s14, s14, 0x70
	v_lshrrev_b32_e32 v2, 4, v53
	s_lshl_b32 s22, s14, 1
	v_or_b32_e32 v3, s14, v2
	v_lshlrev_b32_e32 v4, 4, v51
	v_lshlrev_b32_e32 v2, 2, v2
	s_add_u32 s0, s0, s22
	v_add3_u32 v39, 0, v4, v2
	v_lshlrev_b32_e32 v2, 4, v52
	s_addc_u32 s1, s1, 0
	s_lshr_b32 s14, s7, 3
	v_and_b32_e32 v41, 0xf0, v2
	v_lshlrev_b32_e32 v2, 1, v52
	s_lshl_b64 s[22:23], s[14:15], 18
	v_lshl_or_b32 v51, v3, 2, v4
	v_lshrrev_b32_e32 v4, 3, v54
	v_and_b32_e32 v38, 14, v2
	v_readlane_b32 s25, v253, 48
	v_lshlrev_b32_e32 v2, 6, v4
	v_lshlrev_b32_e32 v3, 2, v38
	s_add_u32 s22, s25, s22
	v_readlane_b32 s25, v253, 49
	s_mul_hi_u32 s24, s14, 0xc00000
	s_mul_i32 s14, s14, 0xc00000
	v_lshlrev_b32_e32 v42, 4, v53
	v_mov_b32_e32 v43, v1
	v_add3_u32 v52, 0, v2, v3
	v_lshlrev_b32_e32 v2, 1, v38
	v_mov_b32_e32 v3, v1
	s_addc_u32 s23, s25, s23
	v_lshlrev_b32_e32 v40, 11, v4
	v_lshl_add_u64 v[2:3], s[0:1], 0, v[2:3]
	v_lshlrev_b32_e32 v4, 12, v4
	v_mov_b32_e32 v5, v1
	v_lshl_add_u64 v[46:47], s[22:23], 0, v[42:43]
	s_add_u32 s22, s78, s14
	v_lshl_add_u64 v[44:45], v[2:3], 0, v[4:5]
	s_addc_u32 s23, s79, s24
	v_mov_b32_e32 v2, v1
	v_mov_b32_e32 v3, v1
	v_mov_b32_e32 v4, v1
	v_mov_b32_e32 v6, v1
	v_mov_b32_e32 v7, v1
	v_lshl_add_u64 v[48:49], s[22:23], 0, v[0:1]
	v_mov_b32_e32 v0, v1
	v_mov_b64_e32 v[8:9], v[6:7]
	v_cmp_gt_u32_e64 s[46:47], 32, v54
	s_mov_b32 s14, -1
	s_movk_i32 s38, 0xf800
	s_mov_b64 s[22:23], 0
	v_mov_b64_e32 v[6:7], v[4:5]
	v_mov_b64_e32 v[4:5], v[2:3]
	v_mov_b64_e32 v[2:3], v[0:1]
	s_add_i32 s100, s72, 0xffffffa0
	s_lshr_b32 s100, s100, 3
	s_lshl_b32 s100, s100, 18
	s_add_u32 s100, s100, 0x37100000
	s_add_u32 s100, s78, s100
	s_addc_u32 s101, s79, 0
	s_nop 3
	v_writelane_b32 v255, s4, 0
	v_writelane_b32 v255, s5, 1
	v_writelane_b32 v255, s6, 2
	v_writelane_b32 v255, s7, 3
	v_writelane_b32 v255, s8, 4
	v_writelane_b32 v255, s9, 5
	v_writelane_b32 v255, s10, 6
	v_writelane_b32 v255, s11, 7
	v_writelane_b32 v255, s28, 8
	v_writelane_b32 v255, s29, 9
	v_writelane_b32 v255, s30, 10
	v_writelane_b32 v255, s31, 11
	v_writelane_b32 v255, s32, 12
	v_writelane_b32 v255, s33, 13
	v_writelane_b32 v255, s34, 14
	v_writelane_b32 v255, s35, 15
	v_writelane_b32 v255, s76, 16
	v_writelane_b32 v255, s77, 17
	v_writelane_b32 v255, s78, 18
	v_writelane_b32 v255, s79, 19
	v_writelane_b32 v255, s80, 20
	v_writelane_b32 v255, s81, 21
	v_writelane_b32 v255, s82, 22
	v_writelane_b32 v255, s83, 23
	v_writelane_b32 v255, s88, 24
	v_writelane_b32 v255, s89, 25
	v_writelane_b32 v255, s90, 26
	v_writelane_b32 v255, s91, 27
	v_writelane_b32 v255, s92, 28
	v_writelane_b32 v255, s93, 29
	v_writelane_b32 v255, s94, 30
	v_writelane_b32 v255, s95, 31
	v_writelane_b32 v255, s96, 32
	v_writelane_b32 v255, s97, 33
	s_load_dwordx8 s[76:83], s[100:101], 0x0
	s_load_dwordx8 s[88:95], s[100:101], 0x20
	s_waitcnt lgkmcnt(0)
	s_barrier
	s_branch .LBB0_824

.LBB0_824:
	s_add_i32 s39, s14, 1
	s_and_saveexec_b64 s[24:25], s[44:45]
	s_xor_b64 s[24:25], exec, s[24:25]
	s_cbranch_execz .LBB0_826
	s_and_b32 s26, s39, 1
	s_mul_i32 s27, s26, 0xc200
	s_add_i32 s27, s27, 0
	v_add_u32_e32 v0, s27, v41
	v_add_u32_e32 v43, s27, v51
	v_mov_b32_e32 v53, s27
	v_lshl_add_u32 v54, s26, 11, v39
	v_add_u32_e32 v55, 0x400, v54
	s_lshl_b32 s96, s39, 9
	s_add_u32 s96, s100, s96
	s_addc_u32 s97, s101, 0
	ds_read_b128 v[56:59], v0 offset:4096
	ds_read_b128 v[60:63], v0 offset:4352
	ds_read_b128 v[64:67], v0 offset:5632
	ds_read_b128 v[68:71], v0 offset:5888
	ds_read2st64_b32 v[104:105], v43 offset0:20 offset1:26
	ds_read_b128 v[88:91], v0 offset:4608
	ds_read_b128 v[92:95], v0 offset:4864
	ds_read_b128 v[96:99], v0 offset:6144
	ds_read_b128 v[100:103], v0 offset:6400
	s_waitcnt lgkmcnt(0)
	s_load_dwordx8 s[28:35], s[96:97], 0x40
	v_mov_b32_e32 v108, s76
	v_pk_mul_f32 v[124:125], v[2:3], v[56:57]
	ds_read_b128 v[72:75], v0 offset:7168
	v_pk_mul_f32 v[126:127], v[2:3], v[88:89]
	ds_read_b128 v[76:79], v0 offset:7424
	v_pk_mul_f32 v[128:129], v[2:3], v[64:65]
	ds_read_b128 v[80:83], v0 offset:8704
	v_pk_mul_f32 v[134:135], v[2:3], v[96:97]
	ds_read_b128 v[84:87], v0 offset:8960
	v_pk_fma_f32 v[124:125], v[4:5], v[58:59], v[124:125]
	ds_read2st64_b32 v[106:107], v43 offset0:32 offset1:38
	v_pk_fma_f32 v[126:127], v[4:5], v[90:91], v[126:127]
	v_pk_fma_f32 v[128:129], v[4:5], v[66:67], v[128:129]
	v_pk_fma_f32 v[134:135], v[4:5], v[98:99], v[134:135]
	v_pk_fma_f32 v[124:125], v[6:7], v[60:61], v[124:125]
	v_pk_fma_f32 v[126:127], v[6:7], v[92:93], v[126:127]
	v_pk_fma_f32 v[128:129], v[6:7], v[68:69], v[128:129]
	v_pk_fma_f32 v[134:135], v[6:7], v[100:101], v[134:135]
	v_pk_fma_f32 v[124:125], v[8:9], v[62:63], v[124:125]
	v_pk_fma_f32 v[126:127], v[8:9], v[94:95], v[126:127]
	v_pk_fma_f32 v[128:129], v[8:9], v[70:71], v[128:129]
	v_pk_fma_f32 v[134:135], v[8:9], v[102:103], v[134:135]
	v_add_f32_e32 v124, v124, v125
	v_add_f32_e32 v126, v126, v127
	v_add_f32_e32 v128, v128, v129
	v_add_f32_e32 v134, v134, v135
	v_mul_f32_e32 v142, s80, v108
	v_add_f32_dpp v125, v124, v124 row_mirror row_mask:0xf bank_mask:0xf
	v_add_f32_dpp v125, v126, v126 row_mirror row_mask:0xf bank_mask:0xc
	v_add_f32_dpp v127, v128, v128 row_mirror row_mask:0xf bank_mask:0xf
	v_add_f32_dpp v127, v134, v134 row_mirror row_mask:0xf bank_mask:0xc
	v_add_f32_dpp v129, v125, v125 row_half_mirror row_mask:0xf bank_mask:0xf
	v_pk_mul_f32 v[2:3], v[2:3], v[142:143] op_sel_hi:[1,0]
	v_pk_mul_f32 v[4:5], v[4:5], v[142:143] op_sel_hi:[1,0]
	v_add_f32_dpp v129, v127, v127 row_half_mirror row_mask:0xf bank_mask:0xa
	v_pk_mul_f32 v[6:7], v[6:7], v[142:143] op_sel_hi:[1,0]
	v_pk_mul_f32 v[8:9], v[8:9], v[142:143] op_sel_hi:[1,0]
	v_add_f32_dpp v129, v129, v129 quad_perm:[1,0,3,2] row_mask:0xf bank_mask:0xf
	ds_read_b128 v[88:91], v0 offset:7680
	ds_read_b128 v[92:95], v0 offset:7936
	v_add_f32_dpp v129, v129, v129 quad_perm:[2,3,0,1] row_mask:0xf bank_mask:0xf
	ds_read_b128 v[96:99], v0 offset:9216
	ds_read_b128 v[100:103], v0 offset:9472
	v_fmac_f32_dpp v104, -v129, v108 row_newbcast:0 row_mask:0xf bank_mask:0xf
	v_mul_f32_dpp v141, v129, v108 row_newbcast:4 row_mask:0xf bank_mask:0xf
	v_mul_f32_e32 v138, s77, v104
	v_mul_f32_dpp v139, v129, v108 row_newbcast:8 row_mask:0xf bank_mask:0xf
	v_fmac_f32_e32 v141, s79, v138
	v_mul_f32_dpp v143, v129, v108 row_newbcast:12 row_mask:0xf bank_mask:0xf
	v_fma_f32 v105, -s80, v141, v105
	v_mul_f32_e32 v144, s80, v138
	v_mul_f32_e32 v140, s81, v105
	v_fmac_f32_e32 v139, s78, v138
	v_pk_fma_f32 v[2:3], v[56:57], v[144:145], v[2:3] op_sel_hi:[1,0,1]
	v_fmac_f32_e32 v143, s83, v138
	v_pk_fma_f32 v[4:5], v[58:59], v[144:145], v[4:5] op_sel_hi:[1,0,1]
	v_pk_fma_f32 v[6:7], v[60:61], v[144:145], v[6:7] op_sel_hi:[1,0,1]
	v_pk_fma_f32 v[8:9], v[62:63], v[144:145], v[8:9] op_sel_hi:[1,0,1]
	v_pk_fma_f32 v[2:3], v[64:65], v[140:141], v[2:3] op_sel_hi:[1,0,1]
	v_pk_fma_f32 v[4:5], v[66:67], v[140:141], v[4:5] op_sel_hi:[1,0,1]
	v_pk_fma_f32 v[6:7], v[68:69], v[140:141], v[6:7] op_sel_hi:[1,0,1]
	v_pk_fma_f32 v[8:9], v[70:71], v[140:141], v[8:9] op_sel_hi:[1,0,1]
	s_waitcnt lgkmcnt(0)
	s_load_dwordx8 s[4:11], s[96:97], 0x60
	v_mov_b32_e32 v108, s88
	v_pk_mul_f32 v[124:125], v[2:3], v[72:73]
	v_mul_f32_e32 v143, s80, v143
	v_pk_mul_f32 v[126:127], v[2:3], v[88:89]
	v_fmac_f32_e32 v143, s82, v140
	v_pk_mul_f32 v[128:129], v[2:3], v[80:81]
	ds_write2_b32 v54, v139, v143 offset0:0 offset1:16
	v_pk_mul_f32 v[134:135], v[2:3], v[96:97]
	ds_read_b128 v[56:59], v0 offset:10240
	v_pk_fma_f32 v[124:125], v[4:5], v[74:75], v[124:125]
	ds_read_b128 v[60:63], v0 offset:10496
	v_pk_fma_f32 v[126:127], v[4:5], v[90:91], v[126:127]
	ds_read_b128 v[64:67], v0 offset:11776
	v_pk_fma_f32 v[128:129], v[4:5], v[82:83], v[128:129]
	ds_read_b128 v[68:71], v0 offset:12032
	v_pk_fma_f32 v[134:135], v[4:5], v[98:99], v[134:135]
	ds_read2st64_b32 v[104:105], v43 offset0:44 offset1:50
	v_pk_fma_f32 v[124:125], v[6:7], v[76:77], v[124:125]
	v_pk_fma_f32 v[126:127], v[6:7], v[92:93], v[126:127]
	v_pk_fma_f32 v[128:129], v[6:7], v[84:85], v[128:129]
	v_pk_fma_f32 v[134:135], v[6:7], v[100:101], v[134:135]
	v_pk_fma_f32 v[124:125], v[8:9], v[78:79], v[124:125]
	v_pk_fma_f32 v[126:127], v[8:9], v[94:95], v[126:127]
	v_pk_fma_f32 v[128:129], v[8:9], v[86:87], v[128:129]
	v_pk_fma_f32 v[134:135], v[8:9], v[102:103], v[134:135]
	v_add_f32_e32 v124, v124, v125
	v_add_f32_e32 v126, v126, v127
	v_add_f32_e32 v128, v128, v129
	v_add_f32_e32 v134, v134, v135
	v_mul_f32_e32 v142, s92, v108
	v_add_f32_dpp v125, v124, v124 row_mirror row_mask:0xf bank_mask:0xf
	v_add_f32_dpp v125, v126, v126 row_mirror row_mask:0xf bank_mask:0xc
	v_add_f32_dpp v127, v128, v128 row_mirror row_mask:0xf bank_mask:0xf
	v_add_f32_dpp v127, v134, v134 row_mirror row_mask:0xf bank_mask:0xc
	v_add_f32_dpp v129, v125, v125 row_half_mirror row_mask:0xf bank_mask:0xf
	v_pk_mul_f32 v[2:3], v[2:3], v[142:143] op_sel_hi:[1,0]
	v_pk_mul_f32 v[4:5], v[4:5], v[142:143] op_sel_hi:[1,0]
	v_add_f32_dpp v129, v127, v127 row_half_mirror row_mask:0xf bank_mask:0xa
	v_pk_mul_f32 v[6:7], v[6:7], v[142:143] op_sel_hi:[1,0]
	v_pk_mul_f32 v[8:9], v[8:9], v[142:143] op_sel_hi:[1,0]
	v_add_f32_dpp v129, v129, v129 quad_perm:[1,0,3,2] row_mask:0xf bank_mask:0xf
	ds_read_b128 v[88:91], v0 offset:10752
	ds_read_b128 v[92:95], v0 offset:11008
	v_add_f32_dpp v129, v129, v129 quad_perm:[2,3,0,1] row_mask:0xf bank_mask:0xf
	ds_read_b128 v[96:99], v0 offset:12288
	ds_read_b128 v[100:103], v0 offset:12544
	v_fmac_f32_dpp v106, -v129, v108 row_newbcast:0 row_mask:0xf bank_mask:0xf
	v_mul_f32_dpp v141, v129, v108 row_newbcast:4 row_mask:0xf bank_mask:0xf
	v_mul_f32_e32 v138, s89, v106
	v_mul_f32_dpp v139, v129, v108 row_newbcast:8 row_mask:0xf bank_mask:0xf
	v_fmac_f32_e32 v141, s91, v138
	v_mul_f32_dpp v143, v129, v108 row_newbcast:12 row_mask:0xf bank_mask:0xf
	v_fma_f32 v107, -s92, v141, v107
	v_mul_f32_e32 v144, s92, v138
	v_mul_f32_e32 v140, s93, v107
	v_fmac_f32_e32 v139, s90, v138
	v_pk_fma_f32 v[2:3], v[72:73], v[144:145], v[2:3] op_sel_hi:[1,0,1]
	v_fmac_f32_e32 v143, s95, v138
	v_pk_fma_f32 v[4:5], v[74:75], v[144:145], v[4:5] op_sel_hi:[1,0,1]
	v_pk_fma_f32 v[6:7], v[76:77], v[144:145], v[6:7] op_sel_hi:[1,0,1]
	v_pk_fma_f32 v[8:9], v[78:79], v[144:145], v[8:9] op_sel_hi:[1,0,1]
	v_pk_fma_f32 v[2:3], v[80:81], v[140:141], v[2:3] op_sel_hi:[1,0,1]
	v_pk_fma_f32 v[4:5], v[82:83], v[140:141], v[4:5] op_sel_hi:[1,0,1]
	v_pk_fma_f32 v[6:7], v[84:85], v[140:141], v[6:7] op_sel_hi:[1,0,1]
	v_pk_fma_f32 v[8:9], v[86:87], v[140:141], v[8:9] op_sel_hi:[1,0,1]
	s_waitcnt lgkmcnt(0)
	s_load_dwordx8 s[76:83], s[96:97], 0x80
	v_mov_b32_e32 v108, s28
	v_pk_mul_f32 v[124:125], v[2:3], v[56:57]
	v_mul_f32_e32 v143, s92, v143
	v_pk_mul_f32 v[126:127], v[2:3], v[88:89]
	v_fmac_f32_e32 v143, s94, v140
	v_pk_mul_f32 v[128:129], v[2:3], v[64:65]
	ds_write2_b32 v54, v139, v143 offset0:32 offset1:48
	v_pk_mul_f32 v[134:135], v[2:3], v[96:97]
	ds_read_b128 v[72:75], v0 offset:13312
	v_pk_fma_f32 v[124:125], v[4:5], v[58:59], v[124:125]
	ds_read_b128 v[76:79], v0 offset:13568
	v_pk_fma_f32 v[126:127], v[4:5], v[90:91], v[126:127]
	ds_read_b128 v[80:83], v0 offset:14848
	v_pk_fma_f32 v[128:129], v[4:5], v[66:67], v[128:129]
	ds_read_b128 v[84:87], v0 offset:15104
	v_pk_fma_f32 v[134:135], v[4:5], v[98:99], v[134:135]
	ds_read2st64_b32 v[106:107], v43 offset0:56 offset1:62
	v_pk_fma_f32 v[124:125], v[6:7], v[60:61], v[124:125]
	v_pk_fma_f32 v[126:127], v[6:7], v[92:93], v[126:127]
	v_pk_fma_f32 v[128:129], v[6:7], v[68:69], v[128:129]
	v_pk_fma_f32 v[134:135], v[6:7], v[100:101], v[134:135]
	v_pk_fma_f32 v[124:125], v[8:9], v[62:63], v[124:125]
	v_pk_fma_f32 v[126:127], v[8:9], v[94:95], v[126:127]
	v_pk_fma_f32 v[128:129], v[8:9], v[70:71], v[128:129]
	v_pk_fma_f32 v[134:135], v[8:9], v[102:103], v[134:135]
	v_add_f32_e32 v124, v124, v125
	v_add_f32_e32 v126, v126, v127
	v_add_f32_e32 v128, v128, v129
	v_add_f32_e32 v134, v134, v135
	v_mul_f32_e32 v142, s32, v108
	v_add_f32_dpp v125, v124, v124 row_mirror row_mask:0xf bank_mask:0xf
	v_add_f32_dpp v125, v126, v126 row_mirror row_mask:0xf bank_mask:0xc
	v_add_f32_dpp v127, v128, v128 row_mirror row_mask:0xf bank_mask:0xf
	v_add_f32_dpp v127, v134, v134 row_mirror row_mask:0xf bank_mask:0xc
	v_add_f32_dpp v129, v125, v125 row_half_mirror row_mask:0xf bank_mask:0xf
	v_pk_mul_f32 v[2:3], v[2:3], v[142:143] op_sel_hi:[1,0]
	v_pk_mul_f32 v[4:5], v[4:5], v[142:143] op_sel_hi:[1,0]
	v_add_f32_dpp v129, v127, v127 row_half_mirror row_mask:0xf bank_mask:0xa
	v_pk_mul_f32 v[6:7], v[6:7], v[142:143] op_sel_hi:[1,0]
	v_pk_mul_f32 v[8:9], v[8:9], v[142:143] op_sel_hi:[1,0]
	v_add_f32_dpp v129, v129, v129 quad_perm:[1,0,3,2] row_mask:0xf bank_mask:0xf
	ds_read_b128 v[88:91], v0 offset:13824
	ds_read_b128 v[92:95], v0 offset:14080
	v_add_f32_dpp v129, v129, v129 quad_perm:[2,3,0,1] row_mask:0xf bank_mask:0xf
	ds_read_b128 v[96:99], v0 offset:15360
	ds_read_b128 v[100:103], v0 offset:15616
	v_fmac_f32_dpp v104, -v129, v108 row_newbcast:0 row_mask:0xf bank_mask:0xf
	v_mul_f32_dpp v141, v129, v108 row_newbcast:4 row_mask:0xf bank_mask:0xf
	v_mul_f32_e32 v138, s29, v104
	v_mul_f32_dpp v139, v129, v108 row_newbcast:8 row_mask:0xf bank_mask:0xf
	v_fmac_f32_e32 v141, s31, v138
	v_mul_f32_dpp v143, v129, v108 row_newbcast:12 row_mask:0xf bank_mask:0xf
	v_fma_f32 v105, -s32, v141, v105
	v_mul_f32_e32 v144, s32, v138
	v_mul_f32_e32 v140, s33, v105
	v_fmac_f32_e32 v139, s30, v138
	v_pk_fma_f32 v[2:3], v[56:57], v[144:145], v[2:3] op_sel_hi:[1,0,1]
	v_fmac_f32_e32 v143, s35, v138
	v_pk_fma_f32 v[4:5], v[58:59], v[144:145], v[4:5] op_sel_hi:[1,0,1]
	v_pk_fma_f32 v[6:7], v[60:61], v[144:145], v[6:7] op_sel_hi:[1,0,1]
	v_pk_fma_f32 v[8:9], v[62:63], v[144:145], v[8:9] op_sel_hi:[1,0,1]
	v_pk_fma_f32 v[2:3], v[64:65], v[140:141], v[2:3] op_sel_hi:[1,0,1]
	v_pk_fma_f32 v[4:5], v[66:67], v[140:141], v[4:5] op_sel_hi:[1,0,1]
	v_pk_fma_f32 v[6:7], v[68:69], v[140:141], v[6:7] op_sel_hi:[1,0,1]
	v_pk_fma_f32 v[8:9], v[70:71], v[140:141], v[8:9] op_sel_hi:[1,0,1]
	s_waitcnt lgkmcnt(0)
	s_load_dwordx8 s[88:95], s[96:97], 0xa0
	v_mov_b32_e32 v108, s4
	v_pk_mul_f32 v[124:125], v[2:3], v[72:73]
	v_mul_f32_e32 v143, s32, v143
	v_pk_mul_f32 v[126:127], v[2:3], v[88:89]
	v_fmac_f32_e32 v143, s34, v140
	v_pk_mul_f32 v[128:129], v[2:3], v[80:81]
	ds_write2_b32 v54, v139, v143 offset0:64 offset1:80
	v_pk_mul_f32 v[134:135], v[2:3], v[96:97]
	ds_read_b128 v[56:59], v0 offset:16384
	v_pk_fma_f32 v[124:125], v[4:5], v[74:75], v[124:125]
	ds_read_b128 v[60:63], v0 offset:16640
	v_pk_fma_f32 v[126:127], v[4:5], v[90:91], v[126:127]
	ds_read_b128 v[64:67], v0 offset:17920
	v_pk_fma_f32 v[128:129], v[4:5], v[82:83], v[128:129]
	ds_read_b128 v[68:71], v0 offset:18176
	v_pk_fma_f32 v[134:135], v[4:5], v[98:99], v[134:135]
	ds_read2st64_b32 v[104:105], v43 offset0:68 offset1:74
	v_pk_fma_f32 v[124:125], v[6:7], v[76:77], v[124:125]
	v_pk_fma_f32 v[126:127], v[6:7], v[92:93], v[126:127]
	v_pk_fma_f32 v[128:129], v[6:7], v[84:85], v[128:129]
	v_pk_fma_f32 v[134:135], v[6:7], v[100:101], v[134:135]
	v_pk_fma_f32 v[124:125], v[8:9], v[78:79], v[124:125]
	v_pk_fma_f32 v[126:127], v[8:9], v[94:95], v[126:127]
	v_pk_fma_f32 v[128:129], v[8:9], v[86:87], v[128:129]
	v_pk_fma_f32 v[134:135], v[8:9], v[102:103], v[134:135]
	v_add_f32_e32 v124, v124, v125
	v_add_f32_e32 v126, v126, v127
	v_add_f32_e32 v128, v128, v129
	v_add_f32_e32 v134, v134, v135
	v_mul_f32_e32 v142, s8, v108
	v_add_f32_dpp v125, v124, v124 row_mirror row_mask:0xf bank_mask:0xf
	v_add_f32_dpp v125, v126, v126 row_mirror row_mask:0xf bank_mask:0xc
	v_add_f32_dpp v127, v128, v128 row_mirror row_mask:0xf bank_mask:0xf
	v_add_f32_dpp v127, v134, v134 row_mirror row_mask:0xf bank_mask:0xc
	v_add_f32_dpp v129, v125, v125 row_half_mirror row_mask:0xf bank_mask:0xf
	v_pk_mul_f32 v[2:3], v[2:3], v[142:143] op_sel_hi:[1,0]
	v_pk_mul_f32 v[4:5], v[4:5], v[142:143] op_sel_hi:[1,0]
	v_add_f32_dpp v129, v127, v127 row_half_mirror row_mask:0xf bank_mask:0xa
	v_pk_mul_f32 v[6:7], v[6:7], v[142:143] op_sel_hi:[1,0]
	v_pk_mul_f32 v[8:9], v[8:9], v[142:143] op_sel_hi:[1,0]
	v_add_f32_dpp v129, v129, v129 quad_perm:[1,0,3,2] row_mask:0xf bank_mask:0xf
	ds_read_b128 v[88:91], v0 offset:16896
	ds_read_b128 v[92:95], v0 offset:17152
	v_add_f32_dpp v129, v129, v129 quad_perm:[2,3,0,1] row_mask:0xf bank_mask:0xf
	ds_read_b128 v[96:99], v0 offset:18432
	ds_read_b128 v[100:103], v0 offset:18688
	v_fmac_f32_dpp v106, -v129, v108 row_newbcast:0 row_mask:0xf bank_mask:0xf
	v_mul_f32_dpp v141, v129, v108 row_newbcast:4 row_mask:0xf bank_mask:0xf
	v_mul_f32_e32 v138, s5, v106
	v_mul_f32_dpp v139, v129, v108 row_newbcast:8 row_mask:0xf bank_mask:0xf
	v_fmac_f32_e32 v141, s7, v138
	v_mul_f32_dpp v143, v129, v108 row_newbcast:12 row_mask:0xf bank_mask:0xf
	v_fma_f32 v107, -s8, v141, v107
	v_mul_f32_e32 v144, s8, v138
	v_mul_f32_e32 v140, s9, v107
	v_fmac_f32_e32 v139, s6, v138
	v_pk_fma_f32 v[2:3], v[72:73], v[144:145], v[2:3] op_sel_hi:[1,0,1]
	v_fmac_f32_e32 v143, s11, v138
	v_pk_fma_f32 v[4:5], v[74:75], v[144:145], v[4:5] op_sel_hi:[1,0,1]
	v_pk_fma_f32 v[6:7], v[76:77], v[144:145], v[6:7] op_sel_hi:[1,0,1]
	v_pk_fma_f32 v[8:9], v[78:79], v[144:145], v[8:9] op_sel_hi:[1,0,1]
	v_pk_fma_f32 v[2:3], v[80:81], v[140:141], v[2:3] op_sel_hi:[1,0,1]
	v_pk_fma_f32 v[4:5], v[82:83], v[140:141], v[4:5] op_sel_hi:[1,0,1]
	v_pk_fma_f32 v[6:7], v[84:85], v[140:141], v[6:7] op_sel_hi:[1,0,1]
	v_pk_fma_f32 v[8:9], v[86:87], v[140:141], v[8:9] op_sel_hi:[1,0,1]
	s_waitcnt lgkmcnt(0)
	s_load_dwordx8 s[28:35], s[96:97], 0xc0
	v_mov_b32_e32 v108, s76
	v_pk_mul_f32 v[124:125], v[2:3], v[56:57]
	v_mul_f32_e32 v143, s8, v143
	v_pk_mul_f32 v[126:127], v[2:3], v[88:89]
	v_fmac_f32_e32 v143, s10, v140
	v_pk_mul_f32 v[128:129], v[2:3], v[64:65]
	ds_write2_b32 v54, v139, v143 offset0:96 offset1:112
	v_pk_mul_f32 v[134:135], v[2:3], v[96:97]
	ds_read_b128 v[72:75], v0 offset:19456
	v_pk_fma_f32 v[124:125], v[4:5], v[58:59], v[124:125]
	ds_read_b128 v[76:79], v0 offset:19712
	v_pk_fma_f32 v[126:127], v[4:5], v[90:91], v[126:127]
	ds_read_b128 v[80:83], v0 offset:20992
	v_pk_fma_f32 v[128:129], v[4:5], v[66:67], v[128:129]
	ds_read_b128 v[84:87], v0 offset:21248
	v_pk_fma_f32 v[134:135], v[4:5], v[98:99], v[134:135]
	ds_read2st64_b32 v[106:107], v43 offset0:80 offset1:86
	v_pk_fma_f32 v[124:125], v[6:7], v[60:61], v[124:125]
	v_pk_fma_f32 v[126:127], v[6:7], v[92:93], v[126:127]
	v_pk_fma_f32 v[128:129], v[6:7], v[68:69], v[128:129]
	v_pk_fma_f32 v[134:135], v[6:7], v[100:101], v[134:135]
	v_pk_fma_f32 v[124:125], v[8:9], v[62:63], v[124:125]
	v_pk_fma_f32 v[126:127], v[8:9], v[94:95], v[126:127]
	v_pk_fma_f32 v[128:129], v[8:9], v[70:71], v[128:129]
	v_pk_fma_f32 v[134:135], v[8:9], v[102:103], v[134:135]
	v_add_f32_e32 v124, v124, v125
	v_add_f32_e32 v126, v126, v127
	v_add_f32_e32 v128, v128, v129
	v_add_f32_e32 v134, v134, v135
	v_mul_f32_e32 v142, s80, v108
	v_add_f32_dpp v125, v124, v124 row_mirror row_mask:0xf bank_mask:0xf
	v_add_f32_dpp v125, v126, v126 row_mirror row_mask:0xf bank_mask:0xc
	v_add_f32_dpp v127, v128, v128 row_mirror row_mask:0xf bank_mask:0xf
	v_add_f32_dpp v127, v134, v134 row_mirror row_mask:0xf bank_mask:0xc
	v_add_f32_dpp v129, v125, v125 row_half_mirror row_mask:0xf bank_mask:0xf
	v_pk_mul_f32 v[2:3], v[2:3], v[142:143] op_sel_hi:[1,0]
	v_pk_mul_f32 v[4:5], v[4:5], v[142:143] op_sel_hi:[1,0]
	v_add_f32_dpp v129, v127, v127 row_half_mirror row_mask:0xf bank_mask:0xa
	v_pk_mul_f32 v[6:7], v[6:7], v[142:143] op_sel_hi:[1,0]
	v_pk_mul_f32 v[8:9], v[8:9], v[142:143] op_sel_hi:[1,0]
	v_add_f32_dpp v129, v129, v129 quad_perm:[1,0,3,2] row_mask:0xf bank_mask:0xf
	ds_read_b128 v[88:91], v0 offset:19968
	ds_read_b128 v[92:95], v0 offset:20224
	v_add_f32_dpp v129, v129, v129 quad_perm:[2,3,0,1] row_mask:0xf bank_mask:0xf
	ds_read_b128 v[96:99], v0 offset:21504
	ds_read_b128 v[100:103], v0 offset:21760
	v_fmac_f32_dpp v104, -v129, v108 row_newbcast:0 row_mask:0xf bank_mask:0xf
	v_mul_f32_dpp v141, v129, v108 row_newbcast:4 row_mask:0xf bank_mask:0xf
	v_mul_f32_e32 v138, s77, v104
	v_mul_f32_dpp v139, v129, v108 row_newbcast:8 row_mask:0xf bank_mask:0xf
	v_fmac_f32_e32 v141, s79, v138
	v_mul_f32_dpp v143, v129, v108 row_newbcast:12 row_mask:0xf bank_mask:0xf
	v_fma_f32 v105, -s80, v141, v105
	v_mul_f32_e32 v144, s80, v138
	v_mul_f32_e32 v140, s81, v105
	v_fmac_f32_e32 v139, s78, v138
	v_pk_fma_f32 v[2:3], v[56:57], v[144:145], v[2:3] op_sel_hi:[1,0,1]
	v_fmac_f32_e32 v143, s83, v138
	v_pk_fma_f32 v[4:5], v[58:59], v[144:145], v[4:5] op_sel_hi:[1,0,1]
	v_pk_fma_f32 v[6:7], v[60:61], v[144:145], v[6:7] op_sel_hi:[1,0,1]
	v_pk_fma_f32 v[8:9], v[62:63], v[144:145], v[8:9] op_sel_hi:[1,0,1]
	v_pk_fma_f32 v[2:3], v[64:65], v[140:141], v[2:3] op_sel_hi:[1,0,1]
	v_pk_fma_f32 v[4:5], v[66:67], v[140:141], v[4:5] op_sel_hi:[1,0,1]
	v_pk_fma_f32 v[6:7], v[68:69], v[140:141], v[6:7] op_sel_hi:[1,0,1]
	v_pk_fma_f32 v[8:9], v[70:71], v[140:141], v[8:9] op_sel_hi:[1,0,1]
	s_waitcnt lgkmcnt(0)
	s_load_dwordx8 s[4:11], s[96:97], 0xe0
	v_mov_b32_e32 v108, s88
	v_pk_mul_f32 v[124:125], v[2:3], v[72:73]
	v_mul_f32_e32 v143, s80, v143
	v_pk_mul_f32 v[126:127], v[2:3], v[88:89]
	v_fmac_f32_e32 v143, s82, v140
	v_pk_mul_f32 v[128:129], v[2:3], v[80:81]
	ds_write2_b32 v54, v139, v143 offset0:128 offset1:144
	v_pk_mul_f32 v[134:135], v[2:3], v[96:97]
	ds_read_b128 v[56:59], v0 offset:22528
	v_pk_fma_f32 v[124:125], v[4:5], v[74:75], v[124:125]
	ds_read_b128 v[60:63], v0 offset:22784
	v_pk_fma_f32 v[126:127], v[4:5], v[90:91], v[126:127]
	ds_read_b128 v[64:67], v0 offset:24064
	v_pk_fma_f32 v[128:129], v[4:5], v[82:83], v[128:129]
	ds_read_b128 v[68:71], v0 offset:24320
	v_pk_fma_f32 v[134:135], v[4:5], v[98:99], v[134:135]
	ds_read2st64_b32 v[104:105], v43 offset0:92 offset1:98
	v_pk_fma_f32 v[124:125], v[6:7], v[76:77], v[124:125]
	v_pk_fma_f32 v[126:127], v[6:7], v[92:93], v[126:127]
	v_pk_fma_f32 v[128:129], v[6:7], v[84:85], v[128:129]
	v_pk_fma_f32 v[134:135], v[6:7], v[100:101], v[134:135]
	v_pk_fma_f32 v[124:125], v[8:9], v[78:79], v[124:125]
	v_pk_fma_f32 v[126:127], v[8:9], v[94:95], v[126:127]
	v_pk_fma_f32 v[128:129], v[8:9], v[86:87], v[128:129]
	v_pk_fma_f32 v[134:135], v[8:9], v[102:103], v[134:135]
	v_add_f32_e32 v124, v124, v125
	v_add_f32_e32 v126, v126, v127
	v_add_f32_e32 v128, v128, v129
	v_add_f32_e32 v134, v134, v135
	v_mul_f32_e32 v142, s92, v108
	v_add_f32_dpp v125, v124, v124 row_mirror row_mask:0xf bank_mask:0xf
	v_add_f32_dpp v125, v126, v126 row_mirror row_mask:0xf bank_mask:0xc
	v_add_f32_dpp v127, v128, v128 row_mirror row_mask:0xf bank_mask:0xf
	v_add_f32_dpp v127, v134, v134 row_mirror row_mask:0xf bank_mask:0xc
	v_add_f32_dpp v129, v125, v125 row_half_mirror row_mask:0xf bank_mask:0xf
	v_pk_mul_f32 v[2:3], v[2:3], v[142:143] op_sel_hi:[1,0]
	v_pk_mul_f32 v[4:5], v[4:5], v[142:143] op_sel_hi:[1,0]
	v_add_f32_dpp v129, v127, v127 row_half_mirror row_mask:0xf bank_mask:0xa
	v_pk_mul_f32 v[6:7], v[6:7], v[142:143] op_sel_hi:[1,0]
	v_pk_mul_f32 v[8:9], v[8:9], v[142:143] op_sel_hi:[1,0]
	v_add_f32_dpp v129, v129, v129 quad_perm:[1,0,3,2] row_mask:0xf bank_mask:0xf
	ds_read_b128 v[88:91], v0 offset:23040
	ds_read_b128 v[92:95], v0 offset:23296
	v_add_f32_dpp v129, v129, v129 quad_perm:[2,3,0,1] row_mask:0xf bank_mask:0xf
	ds_read_b128 v[96:99], v0 offset:24576
	ds_read_b128 v[100:103], v0 offset:24832
	v_fmac_f32_dpp v106, -v129, v108 row_newbcast:0 row_mask:0xf bank_mask:0xf
	v_mul_f32_dpp v141, v129, v108 row_newbcast:4 row_mask:0xf bank_mask:0xf
	v_mul_f32_e32 v138, s89, v106
	v_mul_f32_dpp v139, v129, v108 row_newbcast:8 row_mask:0xf bank_mask:0xf
	v_fmac_f32_e32 v141, s91, v138
	v_mul_f32_dpp v143, v129, v108 row_newbcast:12 row_mask:0xf bank_mask:0xf
	v_fma_f32 v107, -s92, v141, v107
	v_mul_f32_e32 v144, s92, v138
	v_mul_f32_e32 v140, s93, v107
	v_fmac_f32_e32 v139, s90, v138
	v_pk_fma_f32 v[2:3], v[72:73], v[144:145], v[2:3] op_sel_hi:[1,0,1]
	v_fmac_f32_e32 v143, s95, v138
	v_pk_fma_f32 v[4:5], v[74:75], v[144:145], v[4:5] op_sel_hi:[1,0,1]
	v_pk_fma_f32 v[6:7], v[76:77], v[144:145], v[6:7] op_sel_hi:[1,0,1]
	v_pk_fma_f32 v[8:9], v[78:79], v[144:145], v[8:9] op_sel_hi:[1,0,1]
	v_pk_fma_f32 v[2:3], v[80:81], v[140:141], v[2:3] op_sel_hi:[1,0,1]
	v_pk_fma_f32 v[4:5], v[82:83], v[140:141], v[4:5] op_sel_hi:[1,0,1]
	v_pk_fma_f32 v[6:7], v[84:85], v[140:141], v[6:7] op_sel_hi:[1,0,1]
	v_pk_fma_f32 v[8:9], v[86:87], v[140:141], v[8:9] op_sel_hi:[1,0,1]
	s_waitcnt lgkmcnt(0)
	s_load_dwordx8 s[76:83], s[96:97], 0x100
	v_mov_b32_e32 v108, s28
	v_pk_mul_f32 v[124:125], v[2:3], v[56:57]
	v_mul_f32_e32 v143, s92, v143
	v_pk_mul_f32 v[126:127], v[2:3], v[88:89]
	v_fmac_f32_e32 v143, s94, v140
	v_pk_mul_f32 v[128:129], v[2:3], v[64:65]
	ds_write2_b32 v54, v139, v143 offset0:160 offset1:176
	v_pk_mul_f32 v[134:135], v[2:3], v[96:97]
	ds_read_b128 v[72:75], v0 offset:25600
	v_pk_fma_f32 v[124:125], v[4:5], v[58:59], v[124:125]
	ds_read_b128 v[76:79], v0 offset:25856
	v_pk_fma_f32 v[126:127], v[4:5], v[90:91], v[126:127]
	ds_read_b128 v[80:83], v0 offset:27136
	v_pk_fma_f32 v[128:129], v[4:5], v[66:67], v[128:129]
	ds_read_b128 v[84:87], v0 offset:27392
	v_pk_fma_f32 v[134:135], v[4:5], v[98:99], v[134:135]
	ds_read2st64_b32 v[106:107], v43 offset0:104 offset1:110
	v_pk_fma_f32 v[124:125], v[6:7], v[60:61], v[124:125]
	v_pk_fma_f32 v[126:127], v[6:7], v[92:93], v[126:127]
	v_pk_fma_f32 v[128:129], v[6:7], v[68:69], v[128:129]
	v_pk_fma_f32 v[134:135], v[6:7], v[100:101], v[134:135]
	v_pk_fma_f32 v[124:125], v[8:9], v[62:63], v[124:125]
	v_pk_fma_f32 v[126:127], v[8:9], v[94:95], v[126:127]
	v_pk_fma_f32 v[128:129], v[8:9], v[70:71], v[128:129]
	v_pk_fma_f32 v[134:135], v[8:9], v[102:103], v[134:135]
	v_add_f32_e32 v124, v124, v125
	v_add_f32_e32 v126, v126, v127
	v_add_f32_e32 v128, v128, v129
	v_add_f32_e32 v134, v134, v135
	v_mul_f32_e32 v142, s32, v108
	v_add_f32_dpp v125, v124, v124 row_mirror row_mask:0xf bank_mask:0xf
	v_add_f32_dpp v125, v126, v126 row_mirror row_mask:0xf bank_mask:0xc
	v_add_f32_dpp v127, v128, v128 row_mirror row_mask:0xf bank_mask:0xf
	v_add_f32_dpp v127, v134, v134 row_mirror row_mask:0xf bank_mask:0xc
	v_add_f32_dpp v129, v125, v125 row_half_mirror row_mask:0xf bank_mask:0xf
	v_pk_mul_f32 v[2:3], v[2:3], v[142:143] op_sel_hi:[1,0]
	v_pk_mul_f32 v[4:5], v[4:5], v[142:143] op_sel_hi:[1,0]
	v_add_f32_dpp v129, v127, v127 row_half_mirror row_mask:0xf bank_mask:0xa
	v_pk_mul_f32 v[6:7], v[6:7], v[142:143] op_sel_hi:[1,0]
	v_pk_mul_f32 v[8:9], v[8:9], v[142:143] op_sel_hi:[1,0]
	v_add_f32_dpp v129, v129, v129 quad_perm:[1,0,3,2] row_mask:0xf bank_mask:0xf
	ds_read_b128 v[88:91], v0 offset:26112
	ds_read_b128 v[92:95], v0 offset:26368
	v_add_f32_dpp v129, v129, v129 quad_perm:[2,3,0,1] row_mask:0xf bank_mask:0xf
	ds_read_b128 v[96:99], v0 offset:27648
	ds_read_b128 v[100:103], v0 offset:27904
	v_fmac_f32_dpp v104, -v129, v108 row_newbcast:0 row_mask:0xf bank_mask:0xf
	v_mul_f32_dpp v141, v129, v108 row_newbcast:4 row_mask:0xf bank_mask:0xf
	v_mul_f32_e32 v138, s29, v104
	v_mul_f32_dpp v139, v129, v108 row_newbcast:8 row_mask:0xf bank_mask:0xf
	v_fmac_f32_e32 v141, s31, v138
	v_mul_f32_dpp v143, v129, v108 row_newbcast:12 row_mask:0xf bank_mask:0xf
	v_fma_f32 v105, -s32, v141, v105
	v_mul_f32_e32 v144, s32, v138
	v_mul_f32_e32 v140, s33, v105
	v_fmac_f32_e32 v139, s30, v138
	v_pk_fma_f32 v[2:3], v[56:57], v[144:145], v[2:3] op_sel_hi:[1,0,1]
	v_fmac_f32_e32 v143, s35, v138
	v_pk_fma_f32 v[4:5], v[58:59], v[144:145], v[4:5] op_sel_hi:[1,0,1]
	v_pk_fma_f32 v[6:7], v[60:61], v[144:145], v[6:7] op_sel_hi:[1,0,1]
	v_pk_fma_f32 v[8:9], v[62:63], v[144:145], v[8:9] op_sel_hi:[1,0,1]
	v_pk_fma_f32 v[2:3], v[64:65], v[140:141], v[2:3] op_sel_hi:[1,0,1]
	v_pk_fma_f32 v[4:5], v[66:67], v[140:141], v[4:5] op_sel_hi:[1,0,1]
	v_pk_fma_f32 v[6:7], v[68:69], v[140:141], v[6:7] op_sel_hi:[1,0,1]
	v_pk_fma_f32 v[8:9], v[70:71], v[140:141], v[8:9] op_sel_hi:[1,0,1]
	s_waitcnt lgkmcnt(0)
	s_load_dwordx8 s[88:95], s[96:97], 0x120
	v_mov_b32_e32 v108, s4
	v_pk_mul_f32 v[124:125], v[2:3], v[72:73]
	v_mul_f32_e32 v143, s32, v143
	v_pk_mul_f32 v[126:127], v[2:3], v[88:89]
	v_fmac_f32_e32 v143, s34, v140
	v_pk_mul_f32 v[128:129], v[2:3], v[80:81]
	ds_write2_b32 v54, v139, v143 offset0:192 offset1:208
	v_pk_mul_f32 v[134:135], v[2:3], v[96:97]
	ds_read_b128 v[56:59], v0 offset:28672
	v_pk_fma_f32 v[124:125], v[4:5], v[74:75], v[124:125]
	ds_read_b128 v[60:63], v0 offset:28928
	v_pk_fma_f32 v[126:127], v[4:5], v[90:91], v[126:127]
	ds_read_b128 v[64:67], v0 offset:30208
	v_pk_fma_f32 v[128:129], v[4:5], v[82:83], v[128:129]
	ds_read_b128 v[68:71], v0 offset:30464
	v_pk_fma_f32 v[134:135], v[4:5], v[98:99], v[134:135]
	ds_read2st64_b32 v[104:105], v43 offset0:116 offset1:122
	v_pk_fma_f32 v[124:125], v[6:7], v[76:77], v[124:125]
	v_pk_fma_f32 v[126:127], v[6:7], v[92:93], v[126:127]
	v_pk_fma_f32 v[128:129], v[6:7], v[84:85], v[128:129]
	v_pk_fma_f32 v[134:135], v[6:7], v[100:101], v[134:135]
	v_pk_fma_f32 v[124:125], v[8:9], v[78:79], v[124:125]
	v_pk_fma_f32 v[126:127], v[8:9], v[94:95], v[126:127]
	v_pk_fma_f32 v[128:129], v[8:9], v[86:87], v[128:129]
	v_pk_fma_f32 v[134:135], v[8:9], v[102:103], v[134:135]
	v_add_f32_e32 v124, v124, v125
	v_add_f32_e32 v126, v126, v127
	v_add_f32_e32 v128, v128, v129
	v_add_f32_e32 v134, v134, v135
	v_mul_f32_e32 v142, s8, v108
	v_add_f32_dpp v125, v124, v124 row_mirror row_mask:0xf bank_mask:0xf
	v_add_f32_dpp v125, v126, v126 row_mirror row_mask:0xf bank_mask:0xc
	v_add_f32_dpp v127, v128, v128 row_mirror row_mask:0xf bank_mask:0xf
	v_add_f32_dpp v127, v134, v134 row_mirror row_mask:0xf bank_mask:0xc
	v_add_f32_dpp v129, v125, v125 row_half_mirror row_mask:0xf bank_mask:0xf
	v_pk_mul_f32 v[2:3], v[2:3], v[142:143] op_sel_hi:[1,0]
	v_pk_mul_f32 v[4:5], v[4:5], v[142:143] op_sel_hi:[1,0]
	v_add_f32_dpp v129, v127, v127 row_half_mirror row_mask:0xf bank_mask:0xa
	v_pk_mul_f32 v[6:7], v[6:7], v[142:143] op_sel_hi:[1,0]
	v_pk_mul_f32 v[8:9], v[8:9], v[142:143] op_sel_hi:[1,0]
	v_add_f32_dpp v129, v129, v129 quad_perm:[1,0,3,2] row_mask:0xf bank_mask:0xf
	ds_read_b128 v[88:91], v0 offset:29184
	ds_read_b128 v[92:95], v0 offset:29440
	v_add_f32_dpp v129, v129, v129 quad_perm:[2,3,0,1] row_mask:0xf bank_mask:0xf
	ds_read_b128 v[96:99], v0 offset:30720
	ds_read_b128 v[100:103], v0 offset:30976
	v_fmac_f32_dpp v106, -v129, v108 row_newbcast:0 row_mask:0xf bank_mask:0xf
	v_mul_f32_dpp v141, v129, v108 row_newbcast:4 row_mask:0xf bank_mask:0xf
	v_mul_f32_e32 v138, s5, v106
	v_mul_f32_dpp v139, v129, v108 row_newbcast:8 row_mask:0xf bank_mask:0xf
	v_fmac_f32_e32 v141, s7, v138
	v_mul_f32_dpp v143, v129, v108 row_newbcast:12 row_mask:0xf bank_mask:0xf
	v_fma_f32 v107, -s8, v141, v107
	v_mul_f32_e32 v144, s8, v138
	v_mul_f32_e32 v140, s9, v107
	v_fmac_f32_e32 v139, s6, v138
	v_pk_fma_f32 v[2:3], v[72:73], v[144:145], v[2:3] op_sel_hi:[1,0,1]
	v_fmac_f32_e32 v143, s11, v138
	v_pk_fma_f32 v[4:5], v[74:75], v[144:145], v[4:5] op_sel_hi:[1,0,1]
	v_pk_fma_f32 v[6:7], v[76:77], v[144:145], v[6:7] op_sel_hi:[1,0,1]
	v_pk_fma_f32 v[8:9], v[78:79], v[144:145], v[8:9] op_sel_hi:[1,0,1]
	v_pk_fma_f32 v[2:3], v[80:81], v[140:141], v[2:3] op_sel_hi:[1,0,1]
	v_pk_fma_f32 v[4:5], v[82:83], v[140:141], v[4:5] op_sel_hi:[1,0,1]
	v_pk_fma_f32 v[6:7], v[84:85], v[140:141], v[6:7] op_sel_hi:[1,0,1]
	v_pk_fma_f32 v[8:9], v[86:87], v[140:141], v[8:9] op_sel_hi:[1,0,1]
	s_waitcnt lgkmcnt(0)
	s_load_dwordx8 s[28:35], s[96:97], 0x140
	v_mov_b32_e32 v108, s76
	v_pk_mul_f32 v[124:125], v[2:3], v[56:57]
	v_mul_f32_e32 v143, s8, v143
	v_pk_mul_f32 v[126:127], v[2:3], v[88:89]
	v_fmac_f32_e32 v143, s10, v140
	v_pk_mul_f32 v[128:129], v[2:3], v[64:65]
	ds_write2_b32 v54, v139, v143 offset0:224 offset1:240
	v_pk_mul_f32 v[134:135], v[2:3], v[96:97]
	ds_read_b128 v[72:75], v0 offset:31744
	v_pk_fma_f32 v[124:125], v[4:5], v[58:59], v[124:125]
	ds_read_b128 v[76:79], v0 offset:32000
	v_pk_fma_f32 v[126:127], v[4:5], v[90:91], v[126:127]
	ds_read_b128 v[80:83], v0 offset:33280
	v_pk_fma_f32 v[128:129], v[4:5], v[66:67], v[128:129]
	ds_read_b128 v[84:87], v0 offset:33536
	v_pk_fma_f32 v[134:135], v[4:5], v[98:99], v[134:135]
	ds_read2st64_b32 v[106:107], v43 offset0:128 offset1:134
	v_pk_fma_f32 v[124:125], v[6:7], v[60:61], v[124:125]
	v_pk_fma_f32 v[126:127], v[6:7], v[92:93], v[126:127]
	v_pk_fma_f32 v[128:129], v[6:7], v[68:69], v[128:129]
	v_pk_fma_f32 v[134:135], v[6:7], v[100:101], v[134:135]
	v_pk_fma_f32 v[124:125], v[8:9], v[62:63], v[124:125]
	v_pk_fma_f32 v[126:127], v[8:9], v[94:95], v[126:127]
	v_pk_fma_f32 v[128:129], v[8:9], v[70:71], v[128:129]
	v_pk_fma_f32 v[134:135], v[8:9], v[102:103], v[134:135]
	v_add_f32_e32 v124, v124, v125
	v_add_f32_e32 v126, v126, v127
	v_add_f32_e32 v128, v128, v129
	v_add_f32_e32 v134, v134, v135
	v_mul_f32_e32 v142, s80, v108
	v_add_f32_dpp v125, v124, v124 row_mirror row_mask:0xf bank_mask:0xf
	v_add_f32_dpp v125, v126, v126 row_mirror row_mask:0xf bank_mask:0xc
	v_add_f32_dpp v127, v128, v128 row_mirror row_mask:0xf bank_mask:0xf
	v_add_f32_dpp v127, v134, v134 row_mirror row_mask:0xf bank_mask:0xc
	v_add_f32_dpp v129, v125, v125 row_half_mirror row_mask:0xf bank_mask:0xf
	v_pk_mul_f32 v[2:3], v[2:3], v[142:143] op_sel_hi:[1,0]
	v_pk_mul_f32 v[4:5], v[4:5], v[142:143] op_sel_hi:[1,0]
	v_add_f32_dpp v129, v127, v127 row_half_mirror row_mask:0xf bank_mask:0xa
	v_pk_mul_f32 v[6:7], v[6:7], v[142:143] op_sel_hi:[1,0]
	v_pk_mul_f32 v[8:9], v[8:9], v[142:143] op_sel_hi:[1,0]
	v_add_f32_dpp v129, v129, v129 quad_perm:[1,0,3,2] row_mask:0xf bank_mask:0xf
	ds_read_b128 v[88:91], v0 offset:32256
	ds_read_b128 v[92:95], v0 offset:32512
	v_add_f32_dpp v129, v129, v129 quad_perm:[2,3,0,1] row_mask:0xf bank_mask:0xf
	ds_read_b128 v[96:99], v0 offset:33792
	ds_read_b128 v[100:103], v0 offset:34048
	v_fmac_f32_dpp v104, -v129, v108 row_newbcast:0 row_mask:0xf bank_mask:0xf
	v_mul_f32_dpp v141, v129, v108 row_newbcast:4 row_mask:0xf bank_mask:0xf
	v_mul_f32_e32 v138, s77, v104
	v_mul_f32_dpp v139, v129, v108 row_newbcast:8 row_mask:0xf bank_mask:0xf
	v_fmac_f32_e32 v141, s79, v138
	v_mul_f32_dpp v143, v129, v108 row_newbcast:12 row_mask:0xf bank_mask:0xf
	v_fma_f32 v105, -s80, v141, v105
	v_mul_f32_e32 v144, s80, v138
	v_mul_f32_e32 v140, s81, v105
	v_fmac_f32_e32 v139, s78, v138
	v_pk_fma_f32 v[2:3], v[56:57], v[144:145], v[2:3] op_sel_hi:[1,0,1]
	v_fmac_f32_e32 v143, s83, v138
	v_pk_fma_f32 v[4:5], v[58:59], v[144:145], v[4:5] op_sel_hi:[1,0,1]
	v_pk_fma_f32 v[6:7], v[60:61], v[144:145], v[6:7] op_sel_hi:[1,0,1]
	v_pk_fma_f32 v[8:9], v[62:63], v[144:145], v[8:9] op_sel_hi:[1,0,1]
	v_pk_fma_f32 v[2:3], v[64:65], v[140:141], v[2:3] op_sel_hi:[1,0,1]
	v_pk_fma_f32 v[4:5], v[66:67], v[140:141], v[4:5] op_sel_hi:[1,0,1]
	v_pk_fma_f32 v[6:7], v[68:69], v[140:141], v[6:7] op_sel_hi:[1,0,1]
	v_pk_fma_f32 v[8:9], v[70:71], v[140:141], v[8:9] op_sel_hi:[1,0,1]
	s_waitcnt lgkmcnt(0)
	s_load_dwordx8 s[4:11], s[96:97], 0x160
	v_mov_b32_e32 v108, s88
	v_pk_mul_f32 v[124:125], v[2:3], v[72:73]
	v_mul_f32_e32 v143, s80, v143
	v_pk_mul_f32 v[126:127], v[2:3], v[88:89]
	v_fmac_f32_e32 v143, s82, v140
	v_pk_mul_f32 v[128:129], v[2:3], v[80:81]
	ds_write2_b32 v55, v139, v143 offset0:0 offset1:16
	v_pk_mul_f32 v[134:135], v[2:3], v[96:97]
	ds_read_b128 v[56:59], v0 offset:34816
	v_pk_fma_f32 v[124:125], v[4:5], v[74:75], v[124:125]
	ds_read_b128 v[60:63], v0 offset:35072
	v_pk_fma_f32 v[126:127], v[4:5], v[90:91], v[126:127]
	ds_read_b128 v[64:67], v0 offset:36352
	v_pk_fma_f32 v[128:129], v[4:5], v[82:83], v[128:129]
	ds_read_b128 v[68:71], v0 offset:36608
	v_pk_fma_f32 v[134:135], v[4:5], v[98:99], v[134:135]
	ds_read2st64_b32 v[104:105], v43 offset0:140 offset1:146
	v_pk_fma_f32 v[124:125], v[6:7], v[76:77], v[124:125]
	v_pk_fma_f32 v[126:127], v[6:7], v[92:93], v[126:127]
	v_pk_fma_f32 v[128:129], v[6:7], v[84:85], v[128:129]
	v_pk_fma_f32 v[134:135], v[6:7], v[100:101], v[134:135]
	v_pk_fma_f32 v[124:125], v[8:9], v[78:79], v[124:125]
	v_pk_fma_f32 v[126:127], v[8:9], v[94:95], v[126:127]
	v_pk_fma_f32 v[128:129], v[8:9], v[86:87], v[128:129]
	v_pk_fma_f32 v[134:135], v[8:9], v[102:103], v[134:135]
	v_add_f32_e32 v124, v124, v125
	v_add_f32_e32 v126, v126, v127
	v_add_f32_e32 v128, v128, v129
	v_add_f32_e32 v134, v134, v135
	v_mul_f32_e32 v142, s92, v108
	v_add_f32_dpp v125, v124, v124 row_mirror row_mask:0xf bank_mask:0xf
	v_add_f32_dpp v125, v126, v126 row_mirror row_mask:0xf bank_mask:0xc
	v_add_f32_dpp v127, v128, v128 row_mirror row_mask:0xf bank_mask:0xf
	v_add_f32_dpp v127, v134, v134 row_mirror row_mask:0xf bank_mask:0xc
	v_add_f32_dpp v129, v125, v125 row_half_mirror row_mask:0xf bank_mask:0xf
	v_pk_mul_f32 v[2:3], v[2:3], v[142:143] op_sel_hi:[1,0]
	v_pk_mul_f32 v[4:5], v[4:5], v[142:143] op_sel_hi:[1,0]
	v_add_f32_dpp v129, v127, v127 row_half_mirror row_mask:0xf bank_mask:0xa
	v_pk_mul_f32 v[6:7], v[6:7], v[142:143] op_sel_hi:[1,0]
	v_pk_mul_f32 v[8:9], v[8:9], v[142:143] op_sel_hi:[1,0]
	v_add_f32_dpp v129, v129, v129 quad_perm:[1,0,3,2] row_mask:0xf bank_mask:0xf
	ds_read_b128 v[88:91], v0 offset:35328
	ds_read_b128 v[92:95], v0 offset:35584
	v_add_f32_dpp v129, v129, v129 quad_perm:[2,3,0,1] row_mask:0xf bank_mask:0xf
	ds_read_b128 v[96:99], v0 offset:36864
	ds_read_b128 v[100:103], v0 offset:37120
	v_fmac_f32_dpp v106, -v129, v108 row_newbcast:0 row_mask:0xf bank_mask:0xf
	v_mul_f32_dpp v141, v129, v108 row_newbcast:4 row_mask:0xf bank_mask:0xf
	v_mul_f32_e32 v138, s89, v106
	v_mul_f32_dpp v139, v129, v108 row_newbcast:8 row_mask:0xf bank_mask:0xf
	v_fmac_f32_e32 v141, s91, v138
	v_mul_f32_dpp v143, v129, v108 row_newbcast:12 row_mask:0xf bank_mask:0xf
	v_fma_f32 v107, -s92, v141, v107
	v_mul_f32_e32 v144, s92, v138
	v_mul_f32_e32 v140, s93, v107
	v_fmac_f32_e32 v139, s90, v138
	v_pk_fma_f32 v[2:3], v[72:73], v[144:145], v[2:3] op_sel_hi:[1,0,1]
	v_fmac_f32_e32 v143, s95, v138
	v_pk_fma_f32 v[4:5], v[74:75], v[144:145], v[4:5] op_sel_hi:[1,0,1]
	v_pk_fma_f32 v[6:7], v[76:77], v[144:145], v[6:7] op_sel_hi:[1,0,1]
	v_pk_fma_f32 v[8:9], v[78:79], v[144:145], v[8:9] op_sel_hi:[1,0,1]
	v_pk_fma_f32 v[2:3], v[80:81], v[140:141], v[2:3] op_sel_hi:[1,0,1]
	v_pk_fma_f32 v[4:5], v[82:83], v[140:141], v[4:5] op_sel_hi:[1,0,1]
	v_pk_fma_f32 v[6:7], v[84:85], v[140:141], v[6:7] op_sel_hi:[1,0,1]
	v_pk_fma_f32 v[8:9], v[86:87], v[140:141], v[8:9] op_sel_hi:[1,0,1]
	s_waitcnt lgkmcnt(0)
	s_load_dwordx8 s[76:83], s[96:97], 0x180
	v_mov_b32_e32 v108, s28
	v_pk_mul_f32 v[124:125], v[2:3], v[56:57]
	v_mul_f32_e32 v143, s92, v143
	v_pk_mul_f32 v[126:127], v[2:3], v[88:89]
	v_fmac_f32_e32 v143, s94, v140
	v_pk_mul_f32 v[128:129], v[2:3], v[64:65]
	ds_write2_b32 v55, v139, v143 offset0:32 offset1:48
	v_pk_mul_f32 v[134:135], v[2:3], v[96:97]
	ds_read_b128 v[72:75], v0 offset:37888
	v_pk_fma_f32 v[124:125], v[4:5], v[58:59], v[124:125]
	ds_read_b128 v[76:79], v0 offset:38144
	v_pk_fma_f32 v[126:127], v[4:5], v[90:91], v[126:127]
	ds_read_b128 v[80:83], v0 offset:39424
	v_pk_fma_f32 v[128:129], v[4:5], v[66:67], v[128:129]
	ds_read_b128 v[84:87], v0 offset:39680
	v_pk_fma_f32 v[134:135], v[4:5], v[98:99], v[134:135]
	ds_read2st64_b32 v[106:107], v43 offset0:152 offset1:158
	v_pk_fma_f32 v[124:125], v[6:7], v[60:61], v[124:125]
	v_pk_fma_f32 v[126:127], v[6:7], v[92:93], v[126:127]
	v_pk_fma_f32 v[128:129], v[6:7], v[68:69], v[128:129]
	v_pk_fma_f32 v[134:135], v[6:7], v[100:101], v[134:135]
	v_pk_fma_f32 v[124:125], v[8:9], v[62:63], v[124:125]
	v_pk_fma_f32 v[126:127], v[8:9], v[94:95], v[126:127]
	v_pk_fma_f32 v[128:129], v[8:9], v[70:71], v[128:129]
	v_pk_fma_f32 v[134:135], v[8:9], v[102:103], v[134:135]
	v_add_f32_e32 v124, v124, v125
	v_add_f32_e32 v126, v126, v127
	v_add_f32_e32 v128, v128, v129
	v_add_f32_e32 v134, v134, v135
	v_mul_f32_e32 v142, s32, v108
	v_add_f32_dpp v125, v124, v124 row_mirror row_mask:0xf bank_mask:0xf
	v_add_f32_dpp v125, v126, v126 row_mirror row_mask:0xf bank_mask:0xc
	v_add_f32_dpp v127, v128, v128 row_mirror row_mask:0xf bank_mask:0xf
	v_add_f32_dpp v127, v134, v134 row_mirror row_mask:0xf bank_mask:0xc
	v_add_f32_dpp v129, v125, v125 row_half_mirror row_mask:0xf bank_mask:0xf
	v_pk_mul_f32 v[2:3], v[2:3], v[142:143] op_sel_hi:[1,0]
	v_pk_mul_f32 v[4:5], v[4:5], v[142:143] op_sel_hi:[1,0]
	v_add_f32_dpp v129, v127, v127 row_half_mirror row_mask:0xf bank_mask:0xa
	v_pk_mul_f32 v[6:7], v[6:7], v[142:143] op_sel_hi:[1,0]
	v_pk_mul_f32 v[8:9], v[8:9], v[142:143] op_sel_hi:[1,0]
	v_add_f32_dpp v129, v129, v129 quad_perm:[1,0,3,2] row_mask:0xf bank_mask:0xf
	ds_read_b128 v[88:91], v0 offset:38400
	ds_read_b128 v[92:95], v0 offset:38656
	v_add_f32_dpp v129, v129, v129 quad_perm:[2,3,0,1] row_mask:0xf bank_mask:0xf
	ds_read_b128 v[96:99], v0 offset:39936
	ds_read_b128 v[100:103], v0 offset:40192
	v_fmac_f32_dpp v104, -v129, v108 row_newbcast:0 row_mask:0xf bank_mask:0xf
	v_mul_f32_dpp v141, v129, v108 row_newbcast:4 row_mask:0xf bank_mask:0xf
	v_mul_f32_e32 v138, s29, v104
	v_mul_f32_dpp v139, v129, v108 row_newbcast:8 row_mask:0xf bank_mask:0xf
	v_fmac_f32_e32 v141, s31, v138
	v_mul_f32_dpp v143, v129, v108 row_newbcast:12 row_mask:0xf bank_mask:0xf
	v_fma_f32 v105, -s32, v141, v105
	v_mul_f32_e32 v144, s32, v138
	v_mul_f32_e32 v140, s33, v105
	v_fmac_f32_e32 v139, s30, v138
	v_pk_fma_f32 v[2:3], v[56:57], v[144:145], v[2:3] op_sel_hi:[1,0,1]
	v_fmac_f32_e32 v143, s35, v138
	v_pk_fma_f32 v[4:5], v[58:59], v[144:145], v[4:5] op_sel_hi:[1,0,1]
	v_pk_fma_f32 v[6:7], v[60:61], v[144:145], v[6:7] op_sel_hi:[1,0,1]
	v_pk_fma_f32 v[8:9], v[62:63], v[144:145], v[8:9] op_sel_hi:[1,0,1]
	v_pk_fma_f32 v[2:3], v[64:65], v[140:141], v[2:3] op_sel_hi:[1,0,1]
	v_pk_fma_f32 v[4:5], v[66:67], v[140:141], v[4:5] op_sel_hi:[1,0,1]
	v_pk_fma_f32 v[6:7], v[68:69], v[140:141], v[6:7] op_sel_hi:[1,0,1]
	v_pk_fma_f32 v[8:9], v[70:71], v[140:141], v[8:9] op_sel_hi:[1,0,1]
	s_waitcnt lgkmcnt(0)
	s_load_dwordx8 s[88:95], s[96:97], 0x1a0
	v_mov_b32_e32 v108, s4
	v_pk_mul_f32 v[124:125], v[2:3], v[72:73]
	v_mul_f32_e32 v143, s32, v143
	v_pk_mul_f32 v[126:127], v[2:3], v[88:89]
	v_fmac_f32_e32 v143, s34, v140
	v_pk_mul_f32 v[128:129], v[2:3], v[80:81]
	ds_write2_b32 v55, v139, v143 offset0:64 offset1:80
	v_pk_mul_f32 v[134:135], v[2:3], v[96:97]
	ds_read_b128 v[56:59], v0 offset:40960
	v_pk_fma_f32 v[124:125], v[4:5], v[74:75], v[124:125]
	ds_read_b128 v[60:63], v0 offset:41216
	v_pk_fma_f32 v[126:127], v[4:5], v[90:91], v[126:127]
	ds_read_b128 v[64:67], v0 offset:42496
	v_pk_fma_f32 v[128:129], v[4:5], v[82:83], v[128:129]
	ds_read_b128 v[68:71], v0 offset:42752
	v_pk_fma_f32 v[134:135], v[4:5], v[98:99], v[134:135]
	ds_read2st64_b32 v[104:105], v43 offset0:164 offset1:170
	v_pk_fma_f32 v[124:125], v[6:7], v[76:77], v[124:125]
	v_pk_fma_f32 v[126:127], v[6:7], v[92:93], v[126:127]
	v_pk_fma_f32 v[128:129], v[6:7], v[84:85], v[128:129]
	v_pk_fma_f32 v[134:135], v[6:7], v[100:101], v[134:135]
	v_pk_fma_f32 v[124:125], v[8:9], v[78:79], v[124:125]
	v_pk_fma_f32 v[126:127], v[8:9], v[94:95], v[126:127]
	v_pk_fma_f32 v[128:129], v[8:9], v[86:87], v[128:129]
	v_pk_fma_f32 v[134:135], v[8:9], v[102:103], v[134:135]
	v_add_f32_e32 v124, v124, v125
	v_add_f32_e32 v126, v126, v127
	v_add_f32_e32 v128, v128, v129
	v_add_f32_e32 v134, v134, v135
	v_mul_f32_e32 v142, s8, v108
	v_add_f32_dpp v125, v124, v124 row_mirror row_mask:0xf bank_mask:0xf
	v_add_f32_dpp v125, v126, v126 row_mirror row_mask:0xf bank_mask:0xc
	v_add_f32_dpp v127, v128, v128 row_mirror row_mask:0xf bank_mask:0xf
	v_add_f32_dpp v127, v134, v134 row_mirror row_mask:0xf bank_mask:0xc
	v_add_f32_dpp v129, v125, v125 row_half_mirror row_mask:0xf bank_mask:0xf
	v_pk_mul_f32 v[2:3], v[2:3], v[142:143] op_sel_hi:[1,0]
	v_pk_mul_f32 v[4:5], v[4:5], v[142:143] op_sel_hi:[1,0]
	v_add_f32_dpp v129, v127, v127 row_half_mirror row_mask:0xf bank_mask:0xa
	v_pk_mul_f32 v[6:7], v[6:7], v[142:143] op_sel_hi:[1,0]
	v_pk_mul_f32 v[8:9], v[8:9], v[142:143] op_sel_hi:[1,0]
	v_add_f32_dpp v129, v129, v129 quad_perm:[1,0,3,2] row_mask:0xf bank_mask:0xf
	ds_read_b128 v[88:91], v0 offset:41472
	ds_read_b128 v[92:95], v0 offset:41728
	v_add_f32_dpp v129, v129, v129 quad_perm:[2,3,0,1] row_mask:0xf bank_mask:0xf
	ds_read_b128 v[96:99], v0 offset:43008
	ds_read_b128 v[100:103], v0 offset:43264
	v_fmac_f32_dpp v106, -v129, v108 row_newbcast:0 row_mask:0xf bank_mask:0xf
	v_mul_f32_dpp v141, v129, v108 row_newbcast:4 row_mask:0xf bank_mask:0xf
	v_mul_f32_e32 v138, s5, v106
	v_mul_f32_dpp v139, v129, v108 row_newbcast:8 row_mask:0xf bank_mask:0xf
	v_fmac_f32_e32 v141, s7, v138
	v_mul_f32_dpp v143, v129, v108 row_newbcast:12 row_mask:0xf bank_mask:0xf
	v_fma_f32 v107, -s8, v141, v107
	v_mul_f32_e32 v144, s8, v138
	v_mul_f32_e32 v140, s9, v107
	v_fmac_f32_e32 v139, s6, v138
	v_pk_fma_f32 v[2:3], v[72:73], v[144:145], v[2:3] op_sel_hi:[1,0,1]
	v_fmac_f32_e32 v143, s11, v138
	v_pk_fma_f32 v[4:5], v[74:75], v[144:145], v[4:5] op_sel_hi:[1,0,1]
	v_pk_fma_f32 v[6:7], v[76:77], v[144:145], v[6:7] op_sel_hi:[1,0,1]
	v_pk_fma_f32 v[8:9], v[78:79], v[144:145], v[8:9] op_sel_hi:[1,0,1]
	v_pk_fma_f32 v[2:3], v[80:81], v[140:141], v[2:3] op_sel_hi:[1,0,1]
	v_pk_fma_f32 v[4:5], v[82:83], v[140:141], v[4:5] op_sel_hi:[1,0,1]
	v_pk_fma_f32 v[6:7], v[84:85], v[140:141], v[6:7] op_sel_hi:[1,0,1]
	v_pk_fma_f32 v[8:9], v[86:87], v[140:141], v[8:9] op_sel_hi:[1,0,1]
	s_waitcnt lgkmcnt(0)
	s_load_dwordx8 s[28:35], s[96:97], 0x1c0
	v_mov_b32_e32 v108, s76
	v_pk_mul_f32 v[124:125], v[2:3], v[56:57]
	v_mul_f32_e32 v143, s8, v143
	v_pk_mul_f32 v[126:127], v[2:3], v[88:89]
	v_fmac_f32_e32 v143, s10, v140
	v_pk_mul_f32 v[128:129], v[2:3], v[64:65]
	ds_write2_b32 v55, v139, v143 offset0:96 offset1:112
	v_pk_mul_f32 v[134:135], v[2:3], v[96:97]
	ds_read_b128 v[72:75], v0 offset:44032
	v_pk_fma_f32 v[124:125], v[4:5], v[58:59], v[124:125]
	ds_read_b128 v[76:79], v0 offset:44288
	v_pk_fma_f32 v[126:127], v[4:5], v[90:91], v[126:127]
	ds_read_b128 v[80:83], v0 offset:45568
	v_pk_fma_f32 v[128:129], v[4:5], v[66:67], v[128:129]
	ds_read_b128 v[84:87], v0 offset:45824
	v_pk_fma_f32 v[134:135], v[4:5], v[98:99], v[134:135]
	ds_read2st64_b32 v[106:107], v43 offset0:176 offset1:182
	v_pk_fma_f32 v[124:125], v[6:7], v[60:61], v[124:125]
	v_pk_fma_f32 v[126:127], v[6:7], v[92:93], v[126:127]
	v_pk_fma_f32 v[128:129], v[6:7], v[68:69], v[128:129]
	v_pk_fma_f32 v[134:135], v[6:7], v[100:101], v[134:135]
	v_pk_fma_f32 v[124:125], v[8:9], v[62:63], v[124:125]
	v_pk_fma_f32 v[126:127], v[8:9], v[94:95], v[126:127]
	v_pk_fma_f32 v[128:129], v[8:9], v[70:71], v[128:129]
	v_pk_fma_f32 v[134:135], v[8:9], v[102:103], v[134:135]
	v_add_f32_e32 v124, v124, v125
	v_add_f32_e32 v126, v126, v127
	v_add_f32_e32 v128, v128, v129
	v_add_f32_e32 v134, v134, v135
	v_mul_f32_e32 v142, s80, v108
	v_add_f32_dpp v125, v124, v124 row_mirror row_mask:0xf bank_mask:0xf
	v_add_f32_dpp v125, v126, v126 row_mirror row_mask:0xf bank_mask:0xc
	v_add_f32_dpp v127, v128, v128 row_mirror row_mask:0xf bank_mask:0xf
	v_add_f32_dpp v127, v134, v134 row_mirror row_mask:0xf bank_mask:0xc
	v_add_f32_dpp v129, v125, v125 row_half_mirror row_mask:0xf bank_mask:0xf
	v_pk_mul_f32 v[2:3], v[2:3], v[142:143] op_sel_hi:[1,0]
	v_pk_mul_f32 v[4:5], v[4:5], v[142:143] op_sel_hi:[1,0]
	v_add_f32_dpp v129, v127, v127 row_half_mirror row_mask:0xf bank_mask:0xa
	v_pk_mul_f32 v[6:7], v[6:7], v[142:143] op_sel_hi:[1,0]
	v_pk_mul_f32 v[8:9], v[8:9], v[142:143] op_sel_hi:[1,0]
	v_add_f32_dpp v129, v129, v129 quad_perm:[1,0,3,2] row_mask:0xf bank_mask:0xf
	ds_read_b128 v[88:91], v0 offset:44544
	ds_read_b128 v[92:95], v0 offset:44800
	v_add_f32_dpp v129, v129, v129 quad_perm:[2,3,0,1] row_mask:0xf bank_mask:0xf
	ds_read_b128 v[96:99], v0 offset:46080
	ds_read_b128 v[100:103], v0 offset:46336
	v_fmac_f32_dpp v104, -v129, v108 row_newbcast:0 row_mask:0xf bank_mask:0xf
	v_mul_f32_dpp v141, v129, v108 row_newbcast:4 row_mask:0xf bank_mask:0xf
	v_mul_f32_e32 v138, s77, v104
	v_mul_f32_dpp v139, v129, v108 row_newbcast:8 row_mask:0xf bank_mask:0xf
	v_fmac_f32_e32 v141, s79, v138
	v_mul_f32_dpp v143, v129, v108 row_newbcast:12 row_mask:0xf bank_mask:0xf
	v_fma_f32 v105, -s80, v141, v105
	v_mul_f32_e32 v144, s80, v138
	v_mul_f32_e32 v140, s81, v105
	v_fmac_f32_e32 v139, s78, v138
	v_pk_fma_f32 v[2:3], v[56:57], v[144:145], v[2:3] op_sel_hi:[1,0,1]
	v_fmac_f32_e32 v143, s83, v138
	v_pk_fma_f32 v[4:5], v[58:59], v[144:145], v[4:5] op_sel_hi:[1,0,1]
	v_pk_fma_f32 v[6:7], v[60:61], v[144:145], v[6:7] op_sel_hi:[1,0,1]
	v_pk_fma_f32 v[8:9], v[62:63], v[144:145], v[8:9] op_sel_hi:[1,0,1]
	v_pk_fma_f32 v[2:3], v[64:65], v[140:141], v[2:3] op_sel_hi:[1,0,1]
	v_pk_fma_f32 v[4:5], v[66:67], v[140:141], v[4:5] op_sel_hi:[1,0,1]
	v_pk_fma_f32 v[6:7], v[68:69], v[140:141], v[6:7] op_sel_hi:[1,0,1]
	v_pk_fma_f32 v[8:9], v[70:71], v[140:141], v[8:9] op_sel_hi:[1,0,1]
	s_waitcnt lgkmcnt(0)
	s_load_dwordx8 s[4:11], s[96:97], 0x1e0
	v_mov_b32_e32 v108, s88
	v_pk_mul_f32 v[124:125], v[2:3], v[72:73]
	v_mul_f32_e32 v143, s80, v143
	v_pk_mul_f32 v[126:127], v[2:3], v[88:89]
	v_fmac_f32_e32 v143, s82, v140
	v_pk_mul_f32 v[128:129], v[2:3], v[80:81]
	ds_write2_b32 v55, v139, v143 offset0:128 offset1:144
	v_pk_mul_f32 v[134:135], v[2:3], v[96:97]
	ds_read_b128 v[56:59], v0 offset:47104
	v_pk_fma_f32 v[124:125], v[4:5], v[74:75], v[124:125]
	ds_read_b128 v[60:63], v0 offset:47360
	v_pk_fma_f32 v[126:127], v[4:5], v[90:91], v[126:127]
	ds_read_b128 v[64:67], v0 offset:48640
	v_pk_fma_f32 v[128:129], v[4:5], v[82:83], v[128:129]
	ds_read_b128 v[68:71], v0 offset:48896
	v_pk_fma_f32 v[134:135], v[4:5], v[98:99], v[134:135]
	ds_read2st64_b32 v[104:105], v43 offset0:188 offset1:194
	v_pk_fma_f32 v[124:125], v[6:7], v[76:77], v[124:125]
	v_pk_fma_f32 v[126:127], v[6:7], v[92:93], v[126:127]
	v_pk_fma_f32 v[128:129], v[6:7], v[84:85], v[128:129]
	v_pk_fma_f32 v[134:135], v[6:7], v[100:101], v[134:135]
	v_pk_fma_f32 v[124:125], v[8:9], v[78:79], v[124:125]
	v_pk_fma_f32 v[126:127], v[8:9], v[94:95], v[126:127]
	v_pk_fma_f32 v[128:129], v[8:9], v[86:87], v[128:129]
	v_pk_fma_f32 v[134:135], v[8:9], v[102:103], v[134:135]
	v_add_f32_e32 v124, v124, v125
	v_add_f32_e32 v126, v126, v127
	v_add_f32_e32 v128, v128, v129
	v_add_f32_e32 v134, v134, v135
	v_mul_f32_e32 v142, s92, v108
	v_add_f32_dpp v125, v124, v124 row_mirror row_mask:0xf bank_mask:0xf
	v_add_f32_dpp v125, v126, v126 row_mirror row_mask:0xf bank_mask:0xc
	v_add_f32_dpp v127, v128, v128 row_mirror row_mask:0xf bank_mask:0xf
	v_add_f32_dpp v127, v134, v134 row_mirror row_mask:0xf bank_mask:0xc
	v_add_f32_dpp v129, v125, v125 row_half_mirror row_mask:0xf bank_mask:0xf
	v_pk_mul_f32 v[2:3], v[2:3], v[142:143] op_sel_hi:[1,0]
	v_pk_mul_f32 v[4:5], v[4:5], v[142:143] op_sel_hi:[1,0]
	v_add_f32_dpp v129, v127, v127 row_half_mirror row_mask:0xf bank_mask:0xa
	v_pk_mul_f32 v[6:7], v[6:7], v[142:143] op_sel_hi:[1,0]
	v_pk_mul_f32 v[8:9], v[8:9], v[142:143] op_sel_hi:[1,0]
	v_add_f32_dpp v129, v129, v129 quad_perm:[1,0,3,2] row_mask:0xf bank_mask:0xf
	ds_read_b128 v[88:91], v0 offset:47616
	ds_read_b128 v[92:95], v0 offset:47872
	v_add_f32_dpp v129, v129, v129 quad_perm:[2,3,0,1] row_mask:0xf bank_mask:0xf
	ds_read_b128 v[96:99], v0 offset:49152
	ds_read_b128 v[100:103], v0 offset:49408
	v_fmac_f32_dpp v106, -v129, v108 row_newbcast:0 row_mask:0xf bank_mask:0xf
	v_mul_f32_dpp v141, v129, v108 row_newbcast:4 row_mask:0xf bank_mask:0xf
	v_mul_f32_e32 v138, s89, v106
	v_mul_f32_dpp v139, v129, v108 row_newbcast:8 row_mask:0xf bank_mask:0xf
	v_fmac_f32_e32 v141, s91, v138
	v_mul_f32_dpp v143, v129, v108 row_newbcast:12 row_mask:0xf bank_mask:0xf
	v_fma_f32 v107, -s92, v141, v107
	v_mul_f32_e32 v144, s92, v138
	v_mul_f32_e32 v140, s93, v107
	v_fmac_f32_e32 v139, s90, v138
	v_pk_fma_f32 v[2:3], v[72:73], v[144:145], v[2:3] op_sel_hi:[1,0,1]
	v_fmac_f32_e32 v143, s95, v138
	v_pk_fma_f32 v[4:5], v[74:75], v[144:145], v[4:5] op_sel_hi:[1,0,1]
	v_pk_fma_f32 v[6:7], v[76:77], v[144:145], v[6:7] op_sel_hi:[1,0,1]
	v_pk_fma_f32 v[8:9], v[78:79], v[144:145], v[8:9] op_sel_hi:[1,0,1]
	v_pk_fma_f32 v[2:3], v[80:81], v[140:141], v[2:3] op_sel_hi:[1,0,1]
	v_pk_fma_f32 v[4:5], v[82:83], v[140:141], v[4:5] op_sel_hi:[1,0,1]
	v_pk_fma_f32 v[6:7], v[84:85], v[140:141], v[6:7] op_sel_hi:[1,0,1]
	v_pk_fma_f32 v[8:9], v[86:87], v[140:141], v[8:9] op_sel_hi:[1,0,1]
	s_waitcnt lgkmcnt(0)
	s_load_dwordx8 s[76:83], s[96:97], 0x200
	v_mov_b32_e32 v108, s28
	v_pk_mul_f32 v[124:125], v[2:3], v[56:57]
	v_mul_f32_e32 v143, s92, v143
	v_pk_mul_f32 v[126:127], v[2:3], v[88:89]
	v_fmac_f32_e32 v143, s94, v140
	v_pk_mul_f32 v[128:129], v[2:3], v[64:65]
	ds_write2_b32 v55, v139, v143 offset0:160 offset1:176
	v_pk_mul_f32 v[134:135], v[2:3], v[96:97]
	ds_read_b128 v[72:75], v0 offset:50176
	v_pk_fma_f32 v[124:125], v[4:5], v[58:59], v[124:125]
	ds_read_b128 v[76:79], v0 offset:50432
	v_pk_fma_f32 v[126:127], v[4:5], v[90:91], v[126:127]
	ds_read_b128 v[80:83], v0 offset:51712
	v_pk_fma_f32 v[128:129], v[4:5], v[66:67], v[128:129]
	ds_read_b128 v[84:87], v0 offset:51968
	v_pk_fma_f32 v[134:135], v[4:5], v[98:99], v[134:135]
	ds_read2st64_b32 v[106:107], v43 offset0:200 offset1:206
	v_pk_fma_f32 v[124:125], v[6:7], v[60:61], v[124:125]
	v_pk_fma_f32 v[126:127], v[6:7], v[92:93], v[126:127]
	v_pk_fma_f32 v[128:129], v[6:7], v[68:69], v[128:129]
	v_pk_fma_f32 v[134:135], v[6:7], v[100:101], v[134:135]
	v_pk_fma_f32 v[124:125], v[8:9], v[62:63], v[124:125]
	v_pk_fma_f32 v[126:127], v[8:9], v[94:95], v[126:127]
	v_pk_fma_f32 v[128:129], v[8:9], v[70:71], v[128:129]
	v_pk_fma_f32 v[134:135], v[8:9], v[102:103], v[134:135]
	v_add_f32_e32 v124, v124, v125
	v_add_f32_e32 v126, v126, v127
	v_add_f32_e32 v128, v128, v129
	v_add_f32_e32 v134, v134, v135
	v_mul_f32_e32 v142, s32, v108
	v_add_f32_dpp v125, v124, v124 row_mirror row_mask:0xf bank_mask:0xf
	v_add_f32_dpp v125, v126, v126 row_mirror row_mask:0xf bank_mask:0xc
	v_add_f32_dpp v127, v128, v128 row_mirror row_mask:0xf bank_mask:0xf
	v_add_f32_dpp v127, v134, v134 row_mirror row_mask:0xf bank_mask:0xc
	v_add_f32_dpp v129, v125, v125 row_half_mirror row_mask:0xf bank_mask:0xf
	v_pk_mul_f32 v[2:3], v[2:3], v[142:143] op_sel_hi:[1,0]
	v_pk_mul_f32 v[4:5], v[4:5], v[142:143] op_sel_hi:[1,0]
	v_add_f32_dpp v129, v127, v127 row_half_mirror row_mask:0xf bank_mask:0xa
	v_pk_mul_f32 v[6:7], v[6:7], v[142:143] op_sel_hi:[1,0]
	v_pk_mul_f32 v[8:9], v[8:9], v[142:143] op_sel_hi:[1,0]
	v_add_f32_dpp v129, v129, v129 quad_perm:[1,0,3,2] row_mask:0xf bank_mask:0xf
	ds_read_b128 v[88:91], v0 offset:50688
	ds_read_b128 v[92:95], v0 offset:50944
	v_add_f32_dpp v129, v129, v129 quad_perm:[2,3,0,1] row_mask:0xf bank_mask:0xf
	ds_read_b128 v[96:99], v0 offset:52224
	ds_read_b128 v[100:103], v0 offset:52480
	v_fmac_f32_dpp v104, -v129, v108 row_newbcast:0 row_mask:0xf bank_mask:0xf
	v_mul_f32_dpp v141, v129, v108 row_newbcast:4 row_mask:0xf bank_mask:0xf
	v_mul_f32_e32 v138, s29, v104
	v_mul_f32_dpp v139, v129, v108 row_newbcast:8 row_mask:0xf bank_mask:0xf
	v_fmac_f32_e32 v141, s31, v138
	v_mul_f32_dpp v143, v129, v108 row_newbcast:12 row_mask:0xf bank_mask:0xf
	v_fma_f32 v105, -s32, v141, v105
	v_mul_f32_e32 v144, s32, v138
	v_mul_f32_e32 v140, s33, v105
	v_fmac_f32_e32 v139, s30, v138
	v_pk_fma_f32 v[2:3], v[56:57], v[144:145], v[2:3] op_sel_hi:[1,0,1]
	v_fmac_f32_e32 v143, s35, v138
	v_pk_fma_f32 v[4:5], v[58:59], v[144:145], v[4:5] op_sel_hi:[1,0,1]
	v_pk_fma_f32 v[6:7], v[60:61], v[144:145], v[6:7] op_sel_hi:[1,0,1]
	v_pk_fma_f32 v[8:9], v[62:63], v[144:145], v[8:9] op_sel_hi:[1,0,1]
	v_pk_fma_f32 v[2:3], v[64:65], v[140:141], v[2:3] op_sel_hi:[1,0,1]
	v_pk_fma_f32 v[4:5], v[66:67], v[140:141], v[4:5] op_sel_hi:[1,0,1]
	v_pk_fma_f32 v[6:7], v[68:69], v[140:141], v[6:7] op_sel_hi:[1,0,1]
	v_pk_fma_f32 v[8:9], v[70:71], v[140:141], v[8:9] op_sel_hi:[1,0,1]
	s_waitcnt lgkmcnt(0)
	s_load_dwordx8 s[88:95], s[96:97], 0x220
	v_mov_b32_e32 v108, s4
	v_pk_mul_f32 v[124:125], v[2:3], v[72:73]
	v_mul_f32_e32 v143, s32, v143
	v_pk_mul_f32 v[126:127], v[2:3], v[88:89]
	v_fmac_f32_e32 v143, s34, v140
	v_pk_mul_f32 v[128:129], v[2:3], v[80:81]
	ds_write2_b32 v55, v139, v143 offset0:192 offset1:208
	v_pk_mul_f32 v[134:135], v[2:3], v[96:97]
	v_pk_fma_f32 v[124:125], v[4:5], v[74:75], v[124:125]
	v_pk_fma_f32 v[126:127], v[4:5], v[90:91], v[126:127]
	v_pk_fma_f32 v[128:129], v[4:5], v[82:83], v[128:129]
	v_pk_fma_f32 v[134:135], v[4:5], v[98:99], v[134:135]
	v_pk_fma_f32 v[124:125], v[6:7], v[76:77], v[124:125]
	v_pk_fma_f32 v[126:127], v[6:7], v[92:93], v[126:127]
	v_pk_fma_f32 v[128:129], v[6:7], v[84:85], v[128:129]
	v_pk_fma_f32 v[134:135], v[6:7], v[100:101], v[134:135]
	v_pk_fma_f32 v[124:125], v[8:9], v[78:79], v[124:125]
	v_pk_fma_f32 v[126:127], v[8:9], v[94:95], v[126:127]
	v_pk_fma_f32 v[128:129], v[8:9], v[86:87], v[128:129]
	v_pk_fma_f32 v[134:135], v[8:9], v[102:103], v[134:135]
	v_add_f32_e32 v124, v124, v125
	v_add_f32_e32 v126, v126, v127
	v_add_f32_e32 v128, v128, v129
	v_add_f32_e32 v134, v134, v135
	v_mul_f32_e32 v142, s8, v108
	v_add_f32_dpp v125, v124, v124 row_mirror row_mask:0xf bank_mask:0xf
	v_add_f32_dpp v125, v126, v126 row_mirror row_mask:0xf bank_mask:0xc
	v_add_f32_dpp v127, v128, v128 row_mirror row_mask:0xf bank_mask:0xf
	v_add_f32_dpp v127, v134, v134 row_mirror row_mask:0xf bank_mask:0xc
	v_add_f32_dpp v129, v125, v125 row_half_mirror row_mask:0xf bank_mask:0xf
	v_pk_mul_f32 v[2:3], v[2:3], v[142:143] op_sel_hi:[1,0]
	v_pk_mul_f32 v[4:5], v[4:5], v[142:143] op_sel_hi:[1,0]
	v_add_f32_dpp v129, v127, v127 row_half_mirror row_mask:0xf bank_mask:0xa
	v_pk_mul_f32 v[6:7], v[6:7], v[142:143] op_sel_hi:[1,0]
	v_pk_mul_f32 v[8:9], v[8:9], v[142:143] op_sel_hi:[1,0]
	v_add_f32_dpp v129, v129, v129 quad_perm:[1,0,3,2] row_mask:0xf bank_mask:0xf
	s_nop 1
	v_add_f32_dpp v129, v129, v129 quad_perm:[2,3,0,1] row_mask:0xf bank_mask:0xf
	s_nop 1
	v_fmac_f32_dpp v106, -v129, v108 row_newbcast:0 row_mask:0xf bank_mask:0xf
	v_mul_f32_dpp v141, v129, v108 row_newbcast:4 row_mask:0xf bank_mask:0xf
	v_mul_f32_e32 v138, s5, v106
	v_mul_f32_dpp v139, v129, v108 row_newbcast:8 row_mask:0xf bank_mask:0xf
	v_fmac_f32_e32 v141, s7, v138
	v_mul_f32_dpp v143, v129, v108 row_newbcast:12 row_mask:0xf bank_mask:0xf
	v_fma_f32 v107, -s8, v141, v107
	v_mul_f32_e32 v144, s8, v138
	v_mul_f32_e32 v140, s9, v107
	v_fmac_f32_e32 v139, s6, v138
	v_pk_fma_f32 v[2:3], v[72:73], v[144:145], v[2:3] op_sel_hi:[1,0,1]
	v_fmac_f32_e32 v143, s11, v138
	v_pk_fma_f32 v[4:5], v[74:75], v[144:145], v[4:5] op_sel_hi:[1,0,1]
	v_pk_fma_f32 v[6:7], v[76:77], v[144:145], v[6:7] op_sel_hi:[1,0,1]
	v_pk_fma_f32 v[8:9], v[78:79], v[144:145], v[8:9] op_sel_hi:[1,0,1]
	v_pk_fma_f32 v[2:3], v[80:81], v[140:141], v[2:3] op_sel_hi:[1,0,1]
	v_pk_fma_f32 v[4:5], v[82:83], v[140:141], v[4:5] op_sel_hi:[1,0,1]
	v_pk_fma_f32 v[6:7], v[84:85], v[140:141], v[6:7] op_sel_hi:[1,0,1]
	v_pk_fma_f32 v[8:9], v[86:87], v[140:141], v[8:9] op_sel_hi:[1,0,1]
	v_mul_f32_e32 v143, s8, v143
	v_fmac_f32_e32 v143, s10, v140
	ds_write2_b32 v55, v139, v143 offset0:224 offset1:240

.LBB0_836:
	v_readlane_b32 s4, v255, 0
	v_readlane_b32 s5, v255, 1
	v_readlane_b32 s6, v255, 2
	v_readlane_b32 s7, v255, 3
	v_readlane_b32 s8, v255, 4
	v_readlane_b32 s9, v255, 5
	v_readlane_b32 s10, v255, 6
	v_readlane_b32 s11, v255, 7
	v_readlane_b32 s28, v255, 8
	v_readlane_b32 s29, v255, 9
	v_readlane_b32 s30, v255, 10
	v_readlane_b32 s31, v255, 11
	v_readlane_b32 s32, v255, 12
	v_readlane_b32 s33, v255, 13
	v_readlane_b32 s34, v255, 14
	v_readlane_b32 s35, v255, 15
	v_readlane_b32 s76, v255, 16
	v_readlane_b32 s77, v255, 17
	v_readlane_b32 s78, v255, 18
	v_readlane_b32 s79, v255, 19
	v_readlane_b32 s80, v255, 20
	v_readlane_b32 s81, v255, 21
	v_readlane_b32 s82, v255, 22
	v_readlane_b32 s83, v255, 23
	v_readlane_b32 s88, v255, 24
	v_readlane_b32 s89, v255, 25
	v_readlane_b32 s90, v255, 26
	v_readlane_b32 s91, v255, 27
	v_readlane_b32 s92, v255, 28
	v_readlane_b32 s93, v255, 29
	v_readlane_b32 s94, v255, 30
	v_readlane_b32 s95, v255, 31
	v_readlane_b32 s96, v255, 32
	v_readlane_b32 s97, v255, 33
	s_nop 4
	s_and_saveexec_b64 s[22:23], s[42:43]
	s_cbranch_execz .LBB0_838
	ds_read_b64 v[2:3], v52 offset:2048
	v_lshlrev_b32_e32 v0, 1, v40
	s_waitcnt lgkmcnt(0)
	v_cvt_pk_bf16_f32 v4, v2, v3
	v_lshl_add_u64 v[2:3], s[0:1], 0, v[0:1]
	v_lshlrev_b32_e32 v0, 1, v38
	v_lshl_add_u64 v[2:3], v[2:3], 0, v[0:1]
	v_add_co_u32_e32 v2, vcc, 0x3fe0000, v2
	s_nop 1
	v_addc_co_u32_e32 v3, vcc, 0, v3, vcc
	global_store_dword v[2:3], v4, off offset:1536

.LBB0_851:
	s_or_b64 exec, exec, s[22:23]
	s_mul_hi_i32 s0, s38, 0x2aaaaaab
	s_lshr_b32 s1, s0, 31
	s_ashr_i32 s0, s0, 1
	s_add_i32 s40, s0, s1
	s_mul_i32 s0, s40, 12
	s_ashr_i32 s41, s40, 31
	s_and_b32 s26, s72, 3
	s_sub_i32 s22, s38, s0
	s_lshl_b64 s[0:1], s[40:41], 26
	s_add_u32 s27, s78, s0
	s_addc_u32 s41, s79, s1
	s_lshl_b32 s22, s22, 6
	s_ashr_i32 s23, s22, 31
	s_lshl_b64 s[0:1], s[22:23], 1
	s_add_u32 s0, s27, s0
	s_addc_u32 s1, s41, s1
	s_lshl_b32 s23, s26, 5
	s_add_u32 s0, s0, s23
	v_lshrrev_b32_e32 v7, 2, v53
	s_addc_u32 s1, s1, 0
	v_lshlrev_b32_e32 v6, 4, v50
	v_and_b32_e32 v7, 12, v7
	s_lshl_b32 s23, s26, 6
	v_add3_u32 v154, 0, v6, v7
	v_lshlrev_b32_e32 v8, 4, v52
	v_or3_b32 v156, s23, v7, v6
	v_lshlrev_b32_e32 v6, 1, v52
	v_readlane_b32 s23, v253, 51
	v_and_b32_e32 v155, 0xf0, v8
	v_lshrrev_b32_e32 v8, 3, v51
	v_and_b32_e32 v118, 14, v6
	v_cmp_eq_u32_e32 vcc, 3, v50
	s_add_u32 s24, s23, s24
	v_readlane_b32 s23, v253, 52
	v_lshlrev_b32_e32 v122, 4, v53
	v_mov_b32_e32 v123, v1
	v_lshlrev_b32_e32 v6, 6, v8
	v_lshlrev_b32_e32 v7, 2, v118
	v_cndmask_b32_e32 v9, v51, v54, vcc
	s_addc_u32 s25, s23, s25
	v_add3_u32 v157, 0, v6, v7
	v_lshlrev_b32_e32 v6, 1, v118
	v_mov_b32_e32 v7, v1
	v_and_b32_e32 v9, 0xf0, v9
	v_lshl_add_u64 v[126:127], s[24:25], 0, v[122:123]
	s_add_u32 s24, s78, s73
	v_lshlrev_b32_e32 v120, 11, v8
	v_lshl_add_u64 v[6:7], s[0:1], 0, v[6:7]
	v_cmp_eq_u32_e64 s[48:49], 64, v9
	v_lshlrev_b32_e32 v8, 12, v8
	v_mov_b32_e32 v9, v1
	s_addc_u32 s25, s79, s14
	v_mov_b32_e32 v138, 0
	v_cmp_gt_u32_e64 s[46:47], 32, v51
	v_cmp_eq_u16_e64 s[50:51], 64, v46
	v_cmp_eq_u16_e64 s[52:53], 64, v44
	v_cmp_eq_u16_e64 s[54:55], 64, v42
	v_cmp_eq_u16_e64 s[56:57], 64, v40
	v_cmp_eq_u16_e64 s[58:59], 64, v38
	v_cmp_eq_u16_e64 s[60:61], 64, v36
	v_cmp_eq_u16_e64 s[62:63], 64, v34
	v_cmp_eq_u16_e64 s[64:65], 64, v32
	v_cmp_eq_u16_e64 s[66:67], 64, v30
	v_cmp_eq_u16_e64 s[68:69], 64, v28
	v_cmp_eq_u16_e64 s[70:71], 64, v26
	v_lshl_add_u64 v[124:125], v[6:7], 0, v[8:9]
	v_lshl_add_u64 v[128:129], s[24:25], 0, v[0:1]
	s_mov_b32 s14, -1
	s_movk_i32 s23, 0xf800
	s_mov_b64 s[24:25], 0
	v_mov_b32_e32 v139, v138
	v_mov_b32_e32 v140, v138
	v_mov_b32_e32 v141, v138
	s_lshr_b32 s100, s72, 2
	s_lshl_b32 s100, s100, 18
	s_add_u32 s100, s100, 0x2d300000
	s_add_u32 s100, s78, s100
	s_addc_u32 s101, s79, 0
	s_nop 3
	v_writelane_b32 v255, s4, 0
	v_writelane_b32 v255, s5, 1
	v_writelane_b32 v255, s6, 2
	v_writelane_b32 v255, s7, 3
	v_writelane_b32 v255, s8, 4
	v_writelane_b32 v255, s9, 5
	v_writelane_b32 v255, s10, 6
	v_writelane_b32 v255, s11, 7
	v_writelane_b32 v255, s28, 8
	v_writelane_b32 v255, s29, 9
	v_writelane_b32 v255, s30, 10
	v_writelane_b32 v255, s31, 11
	v_writelane_b32 v255, s32, 12
	v_writelane_b32 v255, s33, 13
	v_writelane_b32 v255, s34, 14
	v_writelane_b32 v255, s35, 15
	v_writelane_b32 v255, s76, 16
	v_writelane_b32 v255, s77, 17
	v_writelane_b32 v255, s78, 18
	v_writelane_b32 v255, s79, 19
	v_writelane_b32 v255, s80, 20
	v_writelane_b32 v255, s81, 21
	v_writelane_b32 v255, s82, 22
	v_writelane_b32 v255, s83, 23
	v_writelane_b32 v255, s88, 24
	v_writelane_b32 v255, s89, 25
	v_writelane_b32 v255, s90, 26
	v_writelane_b32 v255, s91, 27
	v_writelane_b32 v255, s92, 28
	v_writelane_b32 v255, s93, 29
	v_writelane_b32 v255, s94, 30
	v_writelane_b32 v255, s95, 31
	v_writelane_b32 v255, s96, 32
	v_writelane_b32 v255, s97, 33
	s_load_dwordx8 s[76:83], s[100:101], 0x0
	s_load_dwordx8 s[88:95], s[100:101], 0x20
	s_waitcnt lgkmcnt(0)
	s_barrier
	s_branch .LBB0_853

.LBB0_853:
	s_add_i32 s41, s14, 1
	s_and_saveexec_b64 s[26:27], s[44:45]
	s_xor_b64 vcc, exec, s[26:27]
	s_cbranch_execz .LBB0_855
	s_and_b32 s26, s41, 1
	s_mul_i32 s27, s26, 0xc200
	s_add_i32 s27, s27, 0
	v_add_u32_e32 v0, s27, v155
	v_add_u32_e32 v158, s27, v156
	v_mov_b32_e32 v123, s27
	v_lshl_add_u32 v159, s26, 11, v154
	v_add_u32_e32 v166, 0x400, v159
	s_lshl_b32 s96, s41, 9
	s_add_u32 s96, s100, s96
	s_addc_u32 s97, s101, 0
	ds_read_b128 v[6:9], v0 offset:4096
	ds_read_b128 v[10:13], v0 offset:4352
	ds_read_b128 v[14:17], v0 offset:4608
	ds_read_b128 v[18:21], v0 offset:4864
	ds_read2st64_b32 v[62:63], v158 offset0:25 offset1:26
	ds_read_b128 v[22:25], v0 offset:5120
	ds_read_b128 v[26:29], v0 offset:5376
	ds_read_b128 v[30:33], v0 offset:5632
	ds_read_b128 v[34:37], v0 offset:5888
	ds_read_b128 v[38:41], v0 offset:6144
	s_waitcnt lgkmcnt(0)
	s_load_dwordx8 s[28:35], s[96:97], 0x40
	v_pk_mul_f32 v[82:83], v[138:139], v[6:7]
	ds_read_b128 v[42:45], v0 offset:8192
	v_pk_mul_f32 v[84:85], v[138:139], v[10:11]
	ds_read_b128 v[46:49], v0 offset:8448
	v_pk_mul_f32 v[86:87], v[138:139], v[14:15]
	ds_read_b128 v[50:53], v0 offset:8704
	v_pk_mul_f32 v[88:89], v[138:139], v[18:19]
	ds_read_b128 v[54:57], v0 offset:8960
	v_pk_fma_f32 v[82:83], v[140:141], v[8:9], v[82:83]
	ds_read_b128 v[58:61], v0 offset:9216
	v_pk_fma_f32 v[84:85], v[140:141], v[12:13], v[84:85]
	ds_read2st64_b32 v[72:73], v158 offset0:37 offset1:38
	v_pk_fma_f32 v[86:87], v[140:141], v[16:17], v[86:87]
	v_pk_fma_f32 v[88:89], v[140:141], v[20:21], v[88:89]
	v_pk_mul_f32 v[138:139], v[138:139], v[22:23]
	v_pk_mul_f32 v[140:141], v[140:141], v[24:25]
	v_add_f32_e32 v82, v82, v83
	v_add_f32_e32 v84, v84, v85
	v_add_f32_e32 v86, v86, v87
	v_add_f32_e32 v88, v88, v89
	ds_read_b128 v[6:9], v0 offset:7168
	ds_read_b128 v[10:13], v0 offset:7424
	ds_read_b128 v[14:17], v0 offset:7680
	ds_read_b128 v[18:21], v0 offset:7936
	v_add_f32_dpp v83, v82, v82 row_mirror row_mask:0xf bank_mask:0xf
	v_add_f32_dpp v83, v84, v84 row_mirror row_mask:0xf bank_mask:0xc
	v_add_f32_dpp v85, v86, v86 row_mirror row_mask:0xf bank_mask:0xf
	v_add_f32_dpp v85, v88, v88 row_mirror row_mask:0xf bank_mask:0xc
	v_add_f32_dpp v87, v83, v83 row_half_mirror row_mask:0xf bank_mask:0xf
	v_pk_fma_f32 v[138:139], v[30:31], v[62:63], v[138:139] op_sel_hi:[1,0,1]
	v_pk_fma_f32 v[140:141], v[32:33], v[62:63], v[140:141] op_sel_hi:[1,0,1]
	v_add_f32_dpp v87, v85, v85 row_half_mirror row_mask:0xf bank_mask:0xa
	v_pk_fma_f32 v[138:139], v[38:39], v[62:63], v[138:139] op_sel:[0,1,0] op_sel_hi:[1,1,1]
	v_pk_fma_f32 v[140:141], v[40:41], v[62:63], v[140:141] op_sel:[0,1,0] op_sel_hi:[1,1,1]
	v_add_f32_dpp v87, v87, v87 quad_perm:[1,0,3,2] row_mask:0xf bank_mask:0xf
	v_mul_f32_e32 v134, s77, v62
	v_mul_f32_e32 v135, s83, v62
	v_add_f32_dpp v87, v87, v87 quad_perm:[2,3,0,1] row_mask:0xf bank_mask:0xf
	v_fmac_f32_e32 v135, s81, v63
	v_mul_f32_e32 v92, s79, v62
	v_mov_b32_dpp v90, v87 row_newbcast:0 row_mask:0xf bank_mask:0xf
	v_add_f32_dpp v92, v87, v92 row_newbcast:4 row_mask:0xf bank_mask:0xf
	v_add_f32_dpp v91, v87, v134 row_newbcast:8 row_mask:0xf bank_mask:0xf
	v_pk_fma_f32 v[138:139], v[26:27], v[90:91], v[138:139] op_sel_hi:[1,0,1] neg_lo:[0,1,0] neg_hi:[0,1,0]
	v_fma_f32 v92, -v90, s78, v92
	v_pk_fma_f32 v[140:141], v[28:29], v[90:91], v[140:141] op_sel_hi:[1,0,1] neg_lo:[0,1,0] neg_hi:[0,1,0]
	v_add_f32_dpp v93, v87, v135 row_newbcast:12 row_mask:0xf bank_mask:0xf
	v_pk_fma_f32 v[138:139], v[34:35], v[92:93], v[138:139] op_sel_hi:[1,0,1] neg_lo:[0,1,0] neg_hi:[0,1,0]
	v_pk_fma_f32 v[140:141], v[36:37], v[92:93], v[140:141] op_sel_hi:[1,0,1] neg_lo:[0,1,0] neg_hi:[0,1,0]
	s_waitcnt lgkmcnt(0)
	s_load_dwordx8 s[4:11], s[96:97], 0x60
	v_pk_mul_f32 v[82:83], v[138:139], v[6:7]
	v_fma_f32 v91, -v90, s76, v91
	v_pk_mul_f32 v[84:85], v[138:139], v[10:11]
	v_fma_f32 v93, -v90, s82, v93
	v_pk_mul_f32 v[86:87], v[138:139], v[14:15]
	v_fma_f32 v93, -v92, s80, v93
	v_pk_mul_f32 v[88:89], v[138:139], v[18:19]
	ds_write2_b32 v159, v91, v93 offset0:0 offset1:16
	v_pk_fma_f32 v[82:83], v[140:141], v[8:9], v[82:83]
	ds_read_b128 v[22:25], v0 offset:11264
	v_pk_fma_f32 v[84:85], v[140:141], v[12:13], v[84:85]
	ds_read_b128 v[26:29], v0 offset:11520
	v_pk_fma_f32 v[86:87], v[140:141], v[16:17], v[86:87]
	ds_read_b128 v[30:33], v0 offset:11776
	v_pk_fma_f32 v[88:89], v[140:141], v[20:21], v[88:89]
	ds_read_b128 v[34:37], v0 offset:12032
	v_pk_mul_f32 v[138:139], v[138:139], v[42:43]
	ds_read_b128 v[38:41], v0 offset:12288
	v_pk_mul_f32 v[140:141], v[140:141], v[44:45]
	ds_read2st64_b32 v[62:63], v158 offset0:49 offset1:50
	v_add_f32_e32 v82, v82, v83
	v_add_f32_e32 v84, v84, v85
	v_add_f32_e32 v86, v86, v87
	v_add_f32_e32 v88, v88, v89
	ds_read_b128 v[6:9], v0 offset:10240
	ds_read_b128 v[10:13], v0 offset:10496
	ds_read_b128 v[14:17], v0 offset:10752
	ds_read_b128 v[18:21], v0 offset:11008
	v_add_f32_dpp v83, v82, v82 row_mirror row_mask:0xf bank_mask:0xf
	v_add_f32_dpp v83, v84, v84 row_mirror row_mask:0xf bank_mask:0xc
	v_add_f32_dpp v85, v86, v86 row_mirror row_mask:0xf bank_mask:0xf
	v_add_f32_dpp v85, v88, v88 row_mirror row_mask:0xf bank_mask:0xc
	v_add_f32_dpp v87, v83, v83 row_half_mirror row_mask:0xf bank_mask:0xf
	v_pk_fma_f32 v[138:139], v[50:51], v[72:73], v[138:139] op_sel_hi:[1,0,1]
	v_pk_fma_f32 v[140:141], v[52:53], v[72:73], v[140:141] op_sel_hi:[1,0,1]
	v_add_f32_dpp v87, v85, v85 row_half_mirror row_mask:0xf bank_mask:0xa
	v_pk_fma_f32 v[138:139], v[58:59], v[72:73], v[138:139] op_sel:[0,1,0] op_sel_hi:[1,1,1]
	v_pk_fma_f32 v[140:141], v[60:61], v[72:73], v[140:141] op_sel:[0,1,0] op_sel_hi:[1,1,1]
	v_add_f32_dpp v87, v87, v87 quad_perm:[1,0,3,2] row_mask:0xf bank_mask:0xf
	v_mul_f32_e32 v134, s89, v72
	v_mul_f32_e32 v135, s95, v72
	v_add_f32_dpp v87, v87, v87 quad_perm:[2,3,0,1] row_mask:0xf bank_mask:0xf
	v_fmac_f32_e32 v135, s93, v73
	v_mul_f32_e32 v92, s91, v72
	v_mov_b32_dpp v90, v87 row_newbcast:0 row_mask:0xf bank_mask:0xf
	v_add_f32_dpp v92, v87, v92 row_newbcast:4 row_mask:0xf bank_mask:0xf
	v_add_f32_dpp v91, v87, v134 row_newbcast:8 row_mask:0xf bank_mask:0xf
	v_pk_fma_f32 v[138:139], v[46:47], v[90:91], v[138:139] op_sel_hi:[1,0,1] neg_lo:[0,1,0] neg_hi:[0,1,0]
	v_fma_f32 v92, -v90, s90, v92
	v_pk_fma_f32 v[140:141], v[48:49], v[90:91], v[140:141] op_sel_hi:[1,0,1] neg_lo:[0,1,0] neg_hi:[0,1,0]
	v_add_f32_dpp v93, v87, v135 row_newbcast:12 row_mask:0xf bank_mask:0xf
	v_pk_fma_f32 v[138:139], v[54:55], v[92:93], v[138:139] op_sel_hi:[1,0,1] neg_lo:[0,1,0] neg_hi:[0,1,0]
	v_pk_fma_f32 v[140:141], v[56:57], v[92:93], v[140:141] op_sel_hi:[1,0,1] neg_lo:[0,1,0] neg_hi:[0,1,0]
	s_waitcnt lgkmcnt(0)
	s_load_dwordx8 s[76:83], s[96:97], 0x80
	v_pk_mul_f32 v[82:83], v[138:139], v[6:7]
	v_fma_f32 v91, -v90, s88, v91
	v_pk_mul_f32 v[84:85], v[138:139], v[10:11]
	v_fma_f32 v93, -v90, s94, v93
	v_pk_mul_f32 v[86:87], v[138:139], v[14:15]
	v_fma_f32 v93, -v92, s92, v93
	v_pk_mul_f32 v[88:89], v[138:139], v[18:19]
	ds_write2_b32 v159, v91, v93 offset0:32 offset1:48
	v_pk_fma_f32 v[82:83], v[140:141], v[8:9], v[82:83]
	ds_read_b128 v[42:45], v0 offset:14336
	v_pk_fma_f32 v[84:85], v[140:141], v[12:13], v[84:85]
	ds_read_b128 v[46:49], v0 offset:14592
	v_pk_fma_f32 v[86:87], v[140:141], v[16:17], v[86:87]
	ds_read_b128 v[50:53], v0 offset:14848
	v_pk_fma_f32 v[88:89], v[140:141], v[20:21], v[88:89]
	ds_read_b128 v[54:57], v0 offset:15104
	v_pk_mul_f32 v[138:139], v[138:139], v[22:23]
	ds_read_b128 v[58:61], v0 offset:15360
	v_pk_mul_f32 v[140:141], v[140:141], v[24:25]
	ds_read2st64_b32 v[72:73], v158 offset0:61 offset1:62
	v_add_f32_e32 v82, v82, v83
	v_add_f32_e32 v84, v84, v85
	v_add_f32_e32 v86, v86, v87
	v_add_f32_e32 v88, v88, v89
	ds_read_b128 v[6:9], v0 offset:13312
	ds_read_b128 v[10:13], v0 offset:13568
	ds_read_b128 v[14:17], v0 offset:13824
	ds_read_b128 v[18:21], v0 offset:14080
	v_add_f32_dpp v83, v82, v82 row_mirror row_mask:0xf bank_mask:0xf
	v_add_f32_dpp v83, v84, v84 row_mirror row_mask:0xf bank_mask:0xc
	v_add_f32_dpp v85, v86, v86 row_mirror row_mask:0xf bank_mask:0xf
	v_add_f32_dpp v85, v88, v88 row_mirror row_mask:0xf bank_mask:0xc
	v_add_f32_dpp v87, v83, v83 row_half_mirror row_mask:0xf bank_mask:0xf
	v_pk_fma_f32 v[138:139], v[30:31], v[62:63], v[138:139] op_sel_hi:[1,0,1]
	v_pk_fma_f32 v[140:141], v[32:33], v[62:63], v[140:141] op_sel_hi:[1,0,1]
	v_add_f32_dpp v87, v85, v85 row_half_mirror row_mask:0xf bank_mask:0xa
	v_pk_fma_f32 v[138:139], v[38:39], v[62:63], v[138:139] op_sel:[0,1,0] op_sel_hi:[1,1,1]
	v_pk_fma_f32 v[140:141], v[40:41], v[62:63], v[140:141] op_sel:[0,1,0] op_sel_hi:[1,1,1]
	v_add_f32_dpp v87, v87, v87 quad_perm:[1,0,3,2] row_mask:0xf bank_mask:0xf
	v_mul_f32_e32 v134, s29, v62
	v_mul_f32_e32 v135, s35, v62
	v_add_f32_dpp v87, v87, v87 quad_perm:[2,3,0,1] row_mask:0xf bank_mask:0xf
	v_fmac_f32_e32 v135, s33, v63
	v_mul_f32_e32 v92, s31, v62
	v_mov_b32_dpp v90, v87 row_newbcast:0 row_mask:0xf bank_mask:0xf
	v_add_f32_dpp v92, v87, v92 row_newbcast:4 row_mask:0xf bank_mask:0xf
	v_add_f32_dpp v91, v87, v134 row_newbcast:8 row_mask:0xf bank_mask:0xf
	v_pk_fma_f32 v[138:139], v[26:27], v[90:91], v[138:139] op_sel_hi:[1,0,1] neg_lo:[0,1,0] neg_hi:[0,1,0]
	v_fma_f32 v92, -v90, s30, v92
	v_pk_fma_f32 v[140:141], v[28:29], v[90:91], v[140:141] op_sel_hi:[1,0,1] neg_lo:[0,1,0] neg_hi:[0,1,0]
	v_add_f32_dpp v93, v87, v135 row_newbcast:12 row_mask:0xf bank_mask:0xf
	v_pk_fma_f32 v[138:139], v[34:35], v[92:93], v[138:139] op_sel_hi:[1,0,1] neg_lo:[0,1,0] neg_hi:[0,1,0]
	v_pk_fma_f32 v[140:141], v[36:37], v[92:93], v[140:141] op_sel_hi:[1,0,1] neg_lo:[0,1,0] neg_hi:[0,1,0]
	s_waitcnt lgkmcnt(0)
	s_load_dwordx8 s[88:95], s[96:97], 0xa0
	v_pk_mul_f32 v[82:83], v[138:139], v[6:7]
	v_fma_f32 v91, -v90, s28, v91
	v_pk_mul_f32 v[84:85], v[138:139], v[10:11]
	v_fma_f32 v93, -v90, s34, v93
	v_pk_mul_f32 v[86:87], v[138:139], v[14:15]
	v_fma_f32 v93, -v92, s32, v93
	v_pk_mul_f32 v[88:89], v[138:139], v[18:19]
	ds_write2_b32 v159, v91, v93 offset0:64 offset1:80
	v_pk_fma_f32 v[82:83], v[140:141], v[8:9], v[82:83]
	ds_read_b128 v[22:25], v0 offset:17408
	v_pk_fma_f32 v[84:85], v[140:141], v[12:13], v[84:85]
	ds_read_b128 v[26:29], v0 offset:17664
	v_pk_fma_f32 v[86:87], v[140:141], v[16:17], v[86:87]
	ds_read_b128 v[30:33], v0 offset:17920
	v_pk_fma_f32 v[88:89], v[140:141], v[20:21], v[88:89]
	ds_read_b128 v[34:37], v0 offset:18176
	v_pk_mul_f32 v[138:139], v[138:139], v[42:43]
	ds_read_b128 v[38:41], v0 offset:18432
	v_pk_mul_f32 v[140:141], v[140:141], v[44:45]
	ds_read2st64_b32 v[62:63], v158 offset0:73 offset1:74
	v_add_f32_e32 v82, v82, v83
	v_add_f32_e32 v84, v84, v85
	v_add_f32_e32 v86, v86, v87
	v_add_f32_e32 v88, v88, v89
	ds_read_b128 v[6:9], v0 offset:16384
	ds_read_b128 v[10:13], v0 offset:16640
	ds_read_b128 v[14:17], v0 offset:16896
	ds_read_b128 v[18:21], v0 offset:17152
	v_add_f32_dpp v83, v82, v82 row_mirror row_mask:0xf bank_mask:0xf
	v_add_f32_dpp v83, v84, v84 row_mirror row_mask:0xf bank_mask:0xc
	v_add_f32_dpp v85, v86, v86 row_mirror row_mask:0xf bank_mask:0xf
	v_add_f32_dpp v85, v88, v88 row_mirror row_mask:0xf bank_mask:0xc
	v_add_f32_dpp v87, v83, v83 row_half_mirror row_mask:0xf bank_mask:0xf
	v_pk_fma_f32 v[138:139], v[50:51], v[72:73], v[138:139] op_sel_hi:[1,0,1]
	v_pk_fma_f32 v[140:141], v[52:53], v[72:73], v[140:141] op_sel_hi:[1,0,1]
	v_add_f32_dpp v87, v85, v85 row_half_mirror row_mask:0xf bank_mask:0xa
	v_pk_fma_f32 v[138:139], v[58:59], v[72:73], v[138:139] op_sel:[0,1,0] op_sel_hi:[1,1,1]
	v_pk_fma_f32 v[140:141], v[60:61], v[72:73], v[140:141] op_sel:[0,1,0] op_sel_hi:[1,1,1]
	v_add_f32_dpp v87, v87, v87 quad_perm:[1,0,3,2] row_mask:0xf bank_mask:0xf
	v_mul_f32_e32 v134, s5, v72
	v_mul_f32_e32 v135, s11, v72
	v_add_f32_dpp v87, v87, v87 quad_perm:[2,3,0,1] row_mask:0xf bank_mask:0xf
	v_fmac_f32_e32 v135, s9, v73
	v_mul_f32_e32 v92, s7, v72
	v_mov_b32_dpp v90, v87 row_newbcast:0 row_mask:0xf bank_mask:0xf
	v_add_f32_dpp v92, v87, v92 row_newbcast:4 row_mask:0xf bank_mask:0xf
	v_add_f32_dpp v91, v87, v134 row_newbcast:8 row_mask:0xf bank_mask:0xf
	v_pk_fma_f32 v[138:139], v[46:47], v[90:91], v[138:139] op_sel_hi:[1,0,1] neg_lo:[0,1,0] neg_hi:[0,1,0]
	v_fma_f32 v92, -v90, s6, v92
	v_pk_fma_f32 v[140:141], v[48:49], v[90:91], v[140:141] op_sel_hi:[1,0,1] neg_lo:[0,1,0] neg_hi:[0,1,0]
	v_add_f32_dpp v93, v87, v135 row_newbcast:12 row_mask:0xf bank_mask:0xf
	v_pk_fma_f32 v[138:139], v[54:55], v[92:93], v[138:139] op_sel_hi:[1,0,1] neg_lo:[0,1,0] neg_hi:[0,1,0]
	v_pk_fma_f32 v[140:141], v[56:57], v[92:93], v[140:141] op_sel_hi:[1,0,1] neg_lo:[0,1,0] neg_hi:[0,1,0]
	s_waitcnt lgkmcnt(0)
	s_load_dwordx8 s[28:35], s[96:97], 0xc0
	v_pk_mul_f32 v[82:83], v[138:139], v[6:7]
	v_fma_f32 v91, -v90, s4, v91
	v_pk_mul_f32 v[84:85], v[138:139], v[10:11]
	v_fma_f32 v93, -v90, s10, v93
	v_pk_mul_f32 v[86:87], v[138:139], v[14:15]
	v_fma_f32 v93, -v92, s8, v93
	v_pk_mul_f32 v[88:89], v[138:139], v[18:19]
	ds_write2_b32 v159, v91, v93 offset0:96 offset1:112
	v_pk_fma_f32 v[82:83], v[140:141], v[8:9], v[82:83]
	ds_read_b128 v[42:45], v0 offset:20480
	v_pk_fma_f32 v[84:85], v[140:141], v[12:13], v[84:85]
	ds_read_b128 v[46:49], v0 offset:20736
	v_pk_fma_f32 v[86:87], v[140:141], v[16:17], v[86:87]
	ds_read_b128 v[50:53], v0 offset:20992
	v_pk_fma_f32 v[88:89], v[140:141], v[20:21], v[88:89]
	ds_read_b128 v[54:57], v0 offset:21248
	v_pk_mul_f32 v[138:139], v[138:139], v[22:23]
	ds_read_b128 v[58:61], v0 offset:21504
	v_pk_mul_f32 v[140:141], v[140:141], v[24:25]
	ds_read2st64_b32 v[72:73], v158 offset0:85 offset1:86
	v_add_f32_e32 v82, v82, v83
	v_add_f32_e32 v84, v84, v85
	v_add_f32_e32 v86, v86, v87
	v_add_f32_e32 v88, v88, v89
	ds_read_b128 v[6:9], v0 offset:19456
	ds_read_b128 v[10:13], v0 offset:19712
	ds_read_b128 v[14:17], v0 offset:19968
	ds_read_b128 v[18:21], v0 offset:20224
	v_add_f32_dpp v83, v82, v82 row_mirror row_mask:0xf bank_mask:0xf
	v_add_f32_dpp v83, v84, v84 row_mirror row_mask:0xf bank_mask:0xc
	v_add_f32_dpp v85, v86, v86 row_mirror row_mask:0xf bank_mask:0xf
	v_add_f32_dpp v85, v88, v88 row_mirror row_mask:0xf bank_mask:0xc
	v_add_f32_dpp v87, v83, v83 row_half_mirror row_mask:0xf bank_mask:0xf
	v_pk_fma_f32 v[138:139], v[30:31], v[62:63], v[138:139] op_sel_hi:[1,0,1]
	v_pk_fma_f32 v[140:141], v[32:33], v[62:63], v[140:141] op_sel_hi:[1,0,1]
	v_add_f32_dpp v87, v85, v85 row_half_mirror row_mask:0xf bank_mask:0xa
	v_pk_fma_f32 v[138:139], v[38:39], v[62:63], v[138:139] op_sel:[0,1,0] op_sel_hi:[1,1,1]
	v_pk_fma_f32 v[140:141], v[40:41], v[62:63], v[140:141] op_sel:[0,1,0] op_sel_hi:[1,1,1]
	v_add_f32_dpp v87, v87, v87 quad_perm:[1,0,3,2] row_mask:0xf bank_mask:0xf
	v_mul_f32_e32 v134, s77, v62
	v_mul_f32_e32 v135, s83, v62
	v_add_f32_dpp v87, v87, v87 quad_perm:[2,3,0,1] row_mask:0xf bank_mask:0xf
	v_fmac_f32_e32 v135, s81, v63
	v_mul_f32_e32 v92, s79, v62
	v_mov_b32_dpp v90, v87 row_newbcast:0 row_mask:0xf bank_mask:0xf
	v_add_f32_dpp v92, v87, v92 row_newbcast:4 row_mask:0xf bank_mask:0xf
	v_add_f32_dpp v91, v87, v134 row_newbcast:8 row_mask:0xf bank_mask:0xf
	v_pk_fma_f32 v[138:139], v[26:27], v[90:91], v[138:139] op_sel_hi:[1,0,1] neg_lo:[0,1,0] neg_hi:[0,1,0]
	v_fma_f32 v92, -v90, s78, v92
	v_pk_fma_f32 v[140:141], v[28:29], v[90:91], v[140:141] op_sel_hi:[1,0,1] neg_lo:[0,1,0] neg_hi:[0,1,0]
	v_add_f32_dpp v93, v87, v135 row_newbcast:12 row_mask:0xf bank_mask:0xf
	v_pk_fma_f32 v[138:139], v[34:35], v[92:93], v[138:139] op_sel_hi:[1,0,1] neg_lo:[0,1,0] neg_hi:[0,1,0]
	v_pk_fma_f32 v[140:141], v[36:37], v[92:93], v[140:141] op_sel_hi:[1,0,1] neg_lo:[0,1,0] neg_hi:[0,1,0]
	s_waitcnt lgkmcnt(0)
	s_load_dwordx8 s[4:11], s[96:97], 0xe0
	v_pk_mul_f32 v[82:83], v[138:139], v[6:7]
	v_fma_f32 v91, -v90, s76, v91
	v_pk_mul_f32 v[84:85], v[138:139], v[10:11]
	v_fma_f32 v93, -v90, s82, v93
	v_pk_mul_f32 v[86:87], v[138:139], v[14:15]
	v_fma_f32 v93, -v92, s80, v93
	v_pk_mul_f32 v[88:89], v[138:139], v[18:19]
	ds_write2_b32 v159, v91, v93 offset0:128 offset1:144
	v_pk_fma_f32 v[82:83], v[140:141], v[8:9], v[82:83]
	ds_read_b128 v[22:25], v0 offset:23552
	v_pk_fma_f32 v[84:85], v[140:141], v[12:13], v[84:85]
	ds_read_b128 v[26:29], v0 offset:23808
	v_pk_fma_f32 v[86:87], v[140:141], v[16:17], v[86:87]
	ds_read_b128 v[30:33], v0 offset:24064
	v_pk_fma_f32 v[88:89], v[140:141], v[20:21], v[88:89]
	ds_read_b128 v[34:37], v0 offset:24320
	v_pk_mul_f32 v[138:139], v[138:139], v[42:43]
	ds_read_b128 v[38:41], v0 offset:24576
	v_pk_mul_f32 v[140:141], v[140:141], v[44:45]
	ds_read2st64_b32 v[62:63], v158 offset0:97 offset1:98
	v_add_f32_e32 v82, v82, v83
	v_add_f32_e32 v84, v84, v85
	v_add_f32_e32 v86, v86, v87
	v_add_f32_e32 v88, v88, v89
	ds_read_b128 v[6:9], v0 offset:22528
	ds_read_b128 v[10:13], v0 offset:22784
	ds_read_b128 v[14:17], v0 offset:23040
	ds_read_b128 v[18:21], v0 offset:23296
	v_add_f32_dpp v83, v82, v82 row_mirror row_mask:0xf bank_mask:0xf
	v_add_f32_dpp v83, v84, v84 row_mirror row_mask:0xf bank_mask:0xc
	v_add_f32_dpp v85, v86, v86 row_mirror row_mask:0xf bank_mask:0xf
	v_add_f32_dpp v85, v88, v88 row_mirror row_mask:0xf bank_mask:0xc
	v_add_f32_dpp v87, v83, v83 row_half_mirror row_mask:0xf bank_mask:0xf
	v_pk_fma_f32 v[138:139], v[50:51], v[72:73], v[138:139] op_sel_hi:[1,0,1]
	v_pk_fma_f32 v[140:141], v[52:53], v[72:73], v[140:141] op_sel_hi:[1,0,1]
	v_add_f32_dpp v87, v85, v85 row_half_mirror row_mask:0xf bank_mask:0xa
	v_pk_fma_f32 v[138:139], v[58:59], v[72:73], v[138:139] op_sel:[0,1,0] op_sel_hi:[1,1,1]
	v_pk_fma_f32 v[140:141], v[60:61], v[72:73], v[140:141] op_sel:[0,1,0] op_sel_hi:[1,1,1]
	v_add_f32_dpp v87, v87, v87 quad_perm:[1,0,3,2] row_mask:0xf bank_mask:0xf
	v_mul_f32_e32 v134, s89, v72
	v_mul_f32_e32 v135, s95, v72
	v_add_f32_dpp v87, v87, v87 quad_perm:[2,3,0,1] row_mask:0xf bank_mask:0xf
	v_fmac_f32_e32 v135, s93, v73
	v_mul_f32_e32 v92, s91, v72
	v_mov_b32_dpp v90, v87 row_newbcast:0 row_mask:0xf bank_mask:0xf
	v_add_f32_dpp v92, v87, v92 row_newbcast:4 row_mask:0xf bank_mask:0xf
	v_add_f32_dpp v91, v87, v134 row_newbcast:8 row_mask:0xf bank_mask:0xf
	v_pk_fma_f32 v[138:139], v[46:47], v[90:91], v[138:139] op_sel_hi:[1,0,1] neg_lo:[0,1,0] neg_hi:[0,1,0]
	v_fma_f32 v92, -v90, s90, v92
	v_pk_fma_f32 v[140:141], v[48:49], v[90:91], v[140:141] op_sel_hi:[1,0,1] neg_lo:[0,1,0] neg_hi:[0,1,0]
	v_add_f32_dpp v93, v87, v135 row_newbcast:12 row_mask:0xf bank_mask:0xf
	v_pk_fma_f32 v[138:139], v[54:55], v[92:93], v[138:139] op_sel_hi:[1,0,1] neg_lo:[0,1,0] neg_hi:[0,1,0]
	v_pk_fma_f32 v[140:141], v[56:57], v[92:93], v[140:141] op_sel_hi:[1,0,1] neg_lo:[0,1,0] neg_hi:[0,1,0]
	s_waitcnt lgkmcnt(0)
	s_load_dwordx8 s[76:83], s[96:97], 0x100
	v_pk_mul_f32 v[82:83], v[138:139], v[6:7]
	v_fma_f32 v91, -v90, s88, v91
	v_pk_mul_f32 v[84:85], v[138:139], v[10:11]
	v_fma_f32 v93, -v90, s94, v93
	v_pk_mul_f32 v[86:87], v[138:139], v[14:15]
	v_fma_f32 v93, -v92, s92, v93
	v_pk_mul_f32 v[88:89], v[138:139], v[18:19]
	ds_write2_b32 v159, v91, v93 offset0:160 offset1:176
	v_pk_fma_f32 v[82:83], v[140:141], v[8:9], v[82:83]
	ds_read_b128 v[42:45], v0 offset:26624
	v_pk_fma_f32 v[84:85], v[140:141], v[12:13], v[84:85]
	ds_read_b128 v[46:49], v0 offset:26880
	v_pk_fma_f32 v[86:87], v[140:141], v[16:17], v[86:87]
	ds_read_b128 v[50:53], v0 offset:27136
	v_pk_fma_f32 v[88:89], v[140:141], v[20:21], v[88:89]
	ds_read_b128 v[54:57], v0 offset:27392
	v_pk_mul_f32 v[138:139], v[138:139], v[22:23]
	ds_read_b128 v[58:61], v0 offset:27648
	v_pk_mul_f32 v[140:141], v[140:141], v[24:25]
	ds_read2st64_b32 v[72:73], v158 offset0:109 offset1:110
	v_add_f32_e32 v82, v82, v83
	v_add_f32_e32 v84, v84, v85
	v_add_f32_e32 v86, v86, v87
	v_add_f32_e32 v88, v88, v89
	ds_read_b128 v[6:9], v0 offset:25600
	ds_read_b128 v[10:13], v0 offset:25856
	ds_read_b128 v[14:17], v0 offset:26112
	ds_read_b128 v[18:21], v0 offset:26368
	v_add_f32_dpp v83, v82, v82 row_mirror row_mask:0xf bank_mask:0xf
	v_add_f32_dpp v83, v84, v84 row_mirror row_mask:0xf bank_mask:0xc
	v_add_f32_dpp v85, v86, v86 row_mirror row_mask:0xf bank_mask:0xf
	v_add_f32_dpp v85, v88, v88 row_mirror row_mask:0xf bank_mask:0xc
	v_add_f32_dpp v87, v83, v83 row_half_mirror row_mask:0xf bank_mask:0xf
	v_pk_fma_f32 v[138:139], v[30:31], v[62:63], v[138:139] op_sel_hi:[1,0,1]
	v_pk_fma_f32 v[140:141], v[32:33], v[62:63], v[140:141] op_sel_hi:[1,0,1]
	v_add_f32_dpp v87, v85, v85 row_half_mirror row_mask:0xf bank_mask:0xa
	v_pk_fma_f32 v[138:139], v[38:39], v[62:63], v[138:139] op_sel:[0,1,0] op_sel_hi:[1,1,1]
	v_pk_fma_f32 v[140:141], v[40:41], v[62:63], v[140:141] op_sel:[0,1,0] op_sel_hi:[1,1,1]
	v_add_f32_dpp v87, v87, v87 quad_perm:[1,0,3,2] row_mask:0xf bank_mask:0xf
	v_mul_f32_e32 v134, s29, v62
	v_mul_f32_e32 v135, s35, v62
	v_add_f32_dpp v87, v87, v87 quad_perm:[2,3,0,1] row_mask:0xf bank_mask:0xf
	v_fmac_f32_e32 v135, s33, v63
	v_mul_f32_e32 v92, s31, v62
	v_mov_b32_dpp v90, v87 row_newbcast:0 row_mask:0xf bank_mask:0xf
	v_add_f32_dpp v92, v87, v92 row_newbcast:4 row_mask:0xf bank_mask:0xf
	v_add_f32_dpp v91, v87, v134 row_newbcast:8 row_mask:0xf bank_mask:0xf
	v_pk_fma_f32 v[138:139], v[26:27], v[90:91], v[138:139] op_sel_hi:[1,0,1] neg_lo:[0,1,0] neg_hi:[0,1,0]
	v_fma_f32 v92, -v90, s30, v92
	v_pk_fma_f32 v[140:141], v[28:29], v[90:91], v[140:141] op_sel_hi:[1,0,1] neg_lo:[0,1,0] neg_hi:[0,1,0]
	v_add_f32_dpp v93, v87, v135 row_newbcast:12 row_mask:0xf bank_mask:0xf
	v_pk_fma_f32 v[138:139], v[34:35], v[92:93], v[138:139] op_sel_hi:[1,0,1] neg_lo:[0,1,0] neg_hi:[0,1,0]
	v_pk_fma_f32 v[140:141], v[36:37], v[92:93], v[140:141] op_sel_hi:[1,0,1] neg_lo:[0,1,0] neg_hi:[0,1,0]
	s_waitcnt lgkmcnt(0)
	s_load_dwordx8 s[88:95], s[96:97], 0x120
	v_pk_mul_f32 v[82:83], v[138:139], v[6:7]
	v_fma_f32 v91, -v90, s28, v91
	v_pk_mul_f32 v[84:85], v[138:139], v[10:11]
	v_fma_f32 v93, -v90, s34, v93
	v_pk_mul_f32 v[86:87], v[138:139], v[14:15]
	v_fma_f32 v93, -v92, s32, v93
	v_pk_mul_f32 v[88:89], v[138:139], v[18:19]
	ds_write2_b32 v159, v91, v93 offset0:192 offset1:208
	v_pk_fma_f32 v[82:83], v[140:141], v[8:9], v[82:83]
	ds_read_b128 v[22:25], v0 offset:29696
	v_pk_fma_f32 v[84:85], v[140:141], v[12:13], v[84:85]
	ds_read_b128 v[26:29], v0 offset:29952
	v_pk_fma_f32 v[86:87], v[140:141], v[16:17], v[86:87]
	ds_read_b128 v[30:33], v0 offset:30208
	v_pk_fma_f32 v[88:89], v[140:141], v[20:21], v[88:89]
	ds_read_b128 v[34:37], v0 offset:30464
	v_pk_mul_f32 v[138:139], v[138:139], v[42:43]
	ds_read_b128 v[38:41], v0 offset:30720
	v_pk_mul_f32 v[140:141], v[140:141], v[44:45]
	ds_read2st64_b32 v[62:63], v158 offset0:121 offset1:122
	v_add_f32_e32 v82, v82, v83
	v_add_f32_e32 v84, v84, v85
	v_add_f32_e32 v86, v86, v87
	v_add_f32_e32 v88, v88, v89
	ds_read_b128 v[6:9], v0 offset:28672
	ds_read_b128 v[10:13], v0 offset:28928
	ds_read_b128 v[14:17], v0 offset:29184
	ds_read_b128 v[18:21], v0 offset:29440
	v_add_f32_dpp v83, v82, v82 row_mirror row_mask:0xf bank_mask:0xf
	v_add_f32_dpp v83, v84, v84 row_mirror row_mask:0xf bank_mask:0xc
	v_add_f32_dpp v85, v86, v86 row_mirror row_mask:0xf bank_mask:0xf
	v_add_f32_dpp v85, v88, v88 row_mirror row_mask:0xf bank_mask:0xc
	v_add_f32_dpp v87, v83, v83 row_half_mirror row_mask:0xf bank_mask:0xf
	v_pk_fma_f32 v[138:139], v[50:51], v[72:73], v[138:139] op_sel_hi:[1,0,1]
	v_pk_fma_f32 v[140:141], v[52:53], v[72:73], v[140:141] op_sel_hi:[1,0,1]
	v_add_f32_dpp v87, v85, v85 row_half_mirror row_mask:0xf bank_mask:0xa
	v_pk_fma_f32 v[138:139], v[58:59], v[72:73], v[138:139] op_sel:[0,1,0] op_sel_hi:[1,1,1]
	v_pk_fma_f32 v[140:141], v[60:61], v[72:73], v[140:141] op_sel:[0,1,0] op_sel_hi:[1,1,1]
	v_add_f32_dpp v87, v87, v87 quad_perm:[1,0,3,2] row_mask:0xf bank_mask:0xf
	v_mul_f32_e32 v134, s5, v72
	v_mul_f32_e32 v135, s11, v72
	v_add_f32_dpp v87, v87, v87 quad_perm:[2,3,0,1] row_mask:0xf bank_mask:0xf
	v_fmac_f32_e32 v135, s9, v73
	v_mul_f32_e32 v92, s7, v72
	v_mov_b32_dpp v90, v87 row_newbcast:0 row_mask:0xf bank_mask:0xf
	v_add_f32_dpp v92, v87, v92 row_newbcast:4 row_mask:0xf bank_mask:0xf
	v_add_f32_dpp v91, v87, v134 row_newbcast:8 row_mask:0xf bank_mask:0xf
	v_pk_fma_f32 v[138:139], v[46:47], v[90:91], v[138:139] op_sel_hi:[1,0,1] neg_lo:[0,1,0] neg_hi:[0,1,0]
	v_fma_f32 v92, -v90, s6, v92
	v_pk_fma_f32 v[140:141], v[48:49], v[90:91], v[140:141] op_sel_hi:[1,0,1] neg_lo:[0,1,0] neg_hi:[0,1,0]
	v_add_f32_dpp v93, v87, v135 row_newbcast:12 row_mask:0xf bank_mask:0xf
	v_pk_fma_f32 v[138:139], v[54:55], v[92:93], v[138:139] op_sel_hi:[1,0,1] neg_lo:[0,1,0] neg_hi:[0,1,0]
	v_pk_fma_f32 v[140:141], v[56:57], v[92:93], v[140:141] op_sel_hi:[1,0,1] neg_lo:[0,1,0] neg_hi:[0,1,0]
	s_waitcnt lgkmcnt(0)
	s_load_dwordx8 s[28:35], s[96:97], 0x140
	v_pk_mul_f32 v[82:83], v[138:139], v[6:7]
	v_fma_f32 v91, -v90, s4, v91
	v_pk_mul_f32 v[84:85], v[138:139], v[10:11]
	v_fma_f32 v93, -v90, s10, v93
	v_pk_mul_f32 v[86:87], v[138:139], v[14:15]
	v_fma_f32 v93, -v92, s8, v93
	v_pk_mul_f32 v[88:89], v[138:139], v[18:19]
	ds_write2_b32 v159, v91, v93 offset0:224 offset1:240
	v_pk_fma_f32 v[82:83], v[140:141], v[8:9], v[82:83]
	ds_read_b128 v[42:45], v0 offset:32768
	v_pk_fma_f32 v[84:85], v[140:141], v[12:13], v[84:85]
	ds_read_b128 v[46:49], v0 offset:33024
	v_pk_fma_f32 v[86:87], v[140:141], v[16:17], v[86:87]
	ds_read_b128 v[50:53], v0 offset:33280
	v_pk_fma_f32 v[88:89], v[140:141], v[20:21], v[88:89]
	ds_read_b128 v[54:57], v0 offset:33536
	v_pk_mul_f32 v[138:139], v[138:139], v[22:23]
	ds_read_b128 v[58:61], v0 offset:33792
	v_pk_mul_f32 v[140:141], v[140:141], v[24:25]
	ds_read2st64_b32 v[72:73], v158 offset0:133 offset1:134
	v_add_f32_e32 v82, v82, v83
	v_add_f32_e32 v84, v84, v85
	v_add_f32_e32 v86, v86, v87
	v_add_f32_e32 v88, v88, v89
	ds_read_b128 v[6:9], v0 offset:31744
	ds_read_b128 v[10:13], v0 offset:32000
	ds_read_b128 v[14:17], v0 offset:32256
	ds_read_b128 v[18:21], v0 offset:32512
	v_add_f32_dpp v83, v82, v82 row_mirror row_mask:0xf bank_mask:0xf
	v_add_f32_dpp v83, v84, v84 row_mirror row_mask:0xf bank_mask:0xc
	v_add_f32_dpp v85, v86, v86 row_mirror row_mask:0xf bank_mask:0xf
	v_add_f32_dpp v85, v88, v88 row_mirror row_mask:0xf bank_mask:0xc
	v_add_f32_dpp v87, v83, v83 row_half_mirror row_mask:0xf bank_mask:0xf
	v_pk_fma_f32 v[138:139], v[30:31], v[62:63], v[138:139] op_sel_hi:[1,0,1]
	v_pk_fma_f32 v[140:141], v[32:33], v[62:63], v[140:141] op_sel_hi:[1,0,1]
	v_add_f32_dpp v87, v85, v85 row_half_mirror row_mask:0xf bank_mask:0xa
	v_pk_fma_f32 v[138:139], v[38:39], v[62:63], v[138:139] op_sel:[0,1,0] op_sel_hi:[1,1,1]
	v_pk_fma_f32 v[140:141], v[40:41], v[62:63], v[140:141] op_sel:[0,1,0] op_sel_hi:[1,1,1]
	v_add_f32_dpp v87, v87, v87 quad_perm:[1,0,3,2] row_mask:0xf bank_mask:0xf
	v_mul_f32_e32 v134, s77, v62
	v_mul_f32_e32 v135, s83, v62
	v_add_f32_dpp v87, v87, v87 quad_perm:[2,3,0,1] row_mask:0xf bank_mask:0xf
	v_fmac_f32_e32 v135, s81, v63
	v_mul_f32_e32 v92, s79, v62
	v_mov_b32_dpp v90, v87 row_newbcast:0 row_mask:0xf bank_mask:0xf
	v_add_f32_dpp v92, v87, v92 row_newbcast:4 row_mask:0xf bank_mask:0xf
	v_add_f32_dpp v91, v87, v134 row_newbcast:8 row_mask:0xf bank_mask:0xf
	v_pk_fma_f32 v[138:139], v[26:27], v[90:91], v[138:139] op_sel_hi:[1,0,1] neg_lo:[0,1,0] neg_hi:[0,1,0]
	v_fma_f32 v92, -v90, s78, v92
	v_pk_fma_f32 v[140:141], v[28:29], v[90:91], v[140:141] op_sel_hi:[1,0,1] neg_lo:[0,1,0] neg_hi:[0,1,0]
	v_add_f32_dpp v93, v87, v135 row_newbcast:12 row_mask:0xf bank_mask:0xf
	v_pk_fma_f32 v[138:139], v[34:35], v[92:93], v[138:139] op_sel_hi:[1,0,1] neg_lo:[0,1,0] neg_hi:[0,1,0]
	v_pk_fma_f32 v[140:141], v[36:37], v[92:93], v[140:141] op_sel_hi:[1,0,1] neg_lo:[0,1,0] neg_hi:[0,1,0]
	s_waitcnt lgkmcnt(0)
	s_load_dwordx8 s[4:11], s[96:97], 0x160
	v_pk_mul_f32 v[82:83], v[138:139], v[6:7]
	v_fma_f32 v91, -v90, s76, v91
	v_pk_mul_f32 v[84:85], v[138:139], v[10:11]
	v_fma_f32 v93, -v90, s82, v93
	v_pk_mul_f32 v[86:87], v[138:139], v[14:15]
	v_fma_f32 v93, -v92, s80, v93
	v_pk_mul_f32 v[88:89], v[138:139], v[18:19]
	ds_write2_b32 v166, v91, v93 offset0:0 offset1:16
	v_pk_fma_f32 v[82:83], v[140:141], v[8:9], v[82:83]
	ds_read_b128 v[22:25], v0 offset:35840
	v_pk_fma_f32 v[84:85], v[140:141], v[12:13], v[84:85]
	ds_read_b128 v[26:29], v0 offset:36096
	v_pk_fma_f32 v[86:87], v[140:141], v[16:17], v[86:87]
	ds_read_b128 v[30:33], v0 offset:36352
	v_pk_fma_f32 v[88:89], v[140:141], v[20:21], v[88:89]
	ds_read_b128 v[34:37], v0 offset:36608
	v_pk_mul_f32 v[138:139], v[138:139], v[42:43]
	ds_read_b128 v[38:41], v0 offset:36864
	v_pk_mul_f32 v[140:141], v[140:141], v[44:45]
	ds_read2st64_b32 v[62:63], v158 offset0:145 offset1:146
	v_add_f32_e32 v82, v82, v83
	v_add_f32_e32 v84, v84, v85
	v_add_f32_e32 v86, v86, v87
	v_add_f32_e32 v88, v88, v89
	ds_read_b128 v[6:9], v0 offset:34816
	ds_read_b128 v[10:13], v0 offset:35072
	ds_read_b128 v[14:17], v0 offset:35328
	ds_read_b128 v[18:21], v0 offset:35584
	v_add_f32_dpp v83, v82, v82 row_mirror row_mask:0xf bank_mask:0xf
	v_add_f32_dpp v83, v84, v84 row_mirror row_mask:0xf bank_mask:0xc
	v_add_f32_dpp v85, v86, v86 row_mirror row_mask:0xf bank_mask:0xf
	v_add_f32_dpp v85, v88, v88 row_mirror row_mask:0xf bank_mask:0xc
	v_add_f32_dpp v87, v83, v83 row_half_mirror row_mask:0xf bank_mask:0xf
	v_pk_fma_f32 v[138:139], v[50:51], v[72:73], v[138:139] op_sel_hi:[1,0,1]
	v_pk_fma_f32 v[140:141], v[52:53], v[72:73], v[140:141] op_sel_hi:[1,0,1]
	v_add_f32_dpp v87, v85, v85 row_half_mirror row_mask:0xf bank_mask:0xa
	v_pk_fma_f32 v[138:139], v[58:59], v[72:73], v[138:139] op_sel:[0,1,0] op_sel_hi:[1,1,1]
	v_pk_fma_f32 v[140:141], v[60:61], v[72:73], v[140:141] op_sel:[0,1,0] op_sel_hi:[1,1,1]
	v_add_f32_dpp v87, v87, v87 quad_perm:[1,0,3,2] row_mask:0xf bank_mask:0xf
	v_mul_f32_e32 v134, s89, v72
	v_mul_f32_e32 v135, s95, v72
	v_add_f32_dpp v87, v87, v87 quad_perm:[2,3,0,1] row_mask:0xf bank_mask:0xf
	v_fmac_f32_e32 v135, s93, v73
	v_mul_f32_e32 v92, s91, v72
	v_mov_b32_dpp v90, v87 row_newbcast:0 row_mask:0xf bank_mask:0xf
	v_add_f32_dpp v92, v87, v92 row_newbcast:4 row_mask:0xf bank_mask:0xf
	v_add_f32_dpp v91, v87, v134 row_newbcast:8 row_mask:0xf bank_mask:0xf
	v_pk_fma_f32 v[138:139], v[46:47], v[90:91], v[138:139] op_sel_hi:[1,0,1] neg_lo:[0,1,0] neg_hi:[0,1,0]
	v_fma_f32 v92, -v90, s90, v92
	v_pk_fma_f32 v[140:141], v[48:49], v[90:91], v[140:141] op_sel_hi:[1,0,1] neg_lo:[0,1,0] neg_hi:[0,1,0]
	v_add_f32_dpp v93, v87, v135 row_newbcast:12 row_mask:0xf bank_mask:0xf
	v_pk_fma_f32 v[138:139], v[54:55], v[92:93], v[138:139] op_sel_hi:[1,0,1] neg_lo:[0,1,0] neg_hi:[0,1,0]
	v_pk_fma_f32 v[140:141], v[56:57], v[92:93], v[140:141] op_sel_hi:[1,0,1] neg_lo:[0,1,0] neg_hi:[0,1,0]
	s_waitcnt lgkmcnt(0)
	s_load_dwordx8 s[76:83], s[96:97], 0x180
	v_pk_mul_f32 v[82:83], v[138:139], v[6:7]
	v_fma_f32 v91, -v90, s88, v91
	v_pk_mul_f32 v[84:85], v[138:139], v[10:11]
	v_fma_f32 v93, -v90, s94, v93
	v_pk_mul_f32 v[86:87], v[138:139], v[14:15]
	v_fma_f32 v93, -v92, s92, v93
	v_pk_mul_f32 v[88:89], v[138:139], v[18:19]
	ds_write2_b32 v166, v91, v93 offset0:32 offset1:48
	v_pk_fma_f32 v[82:83], v[140:141], v[8:9], v[82:83]
	ds_read_b128 v[42:45], v0 offset:38912
	v_pk_fma_f32 v[84:85], v[140:141], v[12:13], v[84:85]
	ds_read_b128 v[46:49], v0 offset:39168
	v_pk_fma_f32 v[86:87], v[140:141], v[16:17], v[86:87]
	ds_read_b128 v[50:53], v0 offset:39424
	v_pk_fma_f32 v[88:89], v[140:141], v[20:21], v[88:89]
	ds_read_b128 v[54:57], v0 offset:39680
	v_pk_mul_f32 v[138:139], v[138:139], v[22:23]
	ds_read_b128 v[58:61], v0 offset:39936
	v_pk_mul_f32 v[140:141], v[140:141], v[24:25]
	ds_read2st64_b32 v[72:73], v158 offset0:157 offset1:158
	v_add_f32_e32 v82, v82, v83
	v_add_f32_e32 v84, v84, v85
	v_add_f32_e32 v86, v86, v87
	v_add_f32_e32 v88, v88, v89
	ds_read_b128 v[6:9], v0 offset:37888
	ds_read_b128 v[10:13], v0 offset:38144
	ds_read_b128 v[14:17], v0 offset:38400
	ds_read_b128 v[18:21], v0 offset:38656
	v_add_f32_dpp v83, v82, v82 row_mirror row_mask:0xf bank_mask:0xf
	v_add_f32_dpp v83, v84, v84 row_mirror row_mask:0xf bank_mask:0xc
	v_add_f32_dpp v85, v86, v86 row_mirror row_mask:0xf bank_mask:0xf
	v_add_f32_dpp v85, v88, v88 row_mirror row_mask:0xf bank_mask:0xc
	v_add_f32_dpp v87, v83, v83 row_half_mirror row_mask:0xf bank_mask:0xf
	v_pk_fma_f32 v[138:139], v[30:31], v[62:63], v[138:139] op_sel_hi:[1,0,1]
	v_pk_fma_f32 v[140:141], v[32:33], v[62:63], v[140:141] op_sel_hi:[1,0,1]
	v_add_f32_dpp v87, v85, v85 row_half_mirror row_mask:0xf bank_mask:0xa
	v_pk_fma_f32 v[138:139], v[38:39], v[62:63], v[138:139] op_sel:[0,1,0] op_sel_hi:[1,1,1]
	v_pk_fma_f32 v[140:141], v[40:41], v[62:63], v[140:141] op_sel:[0,1,0] op_sel_hi:[1,1,1]
	v_add_f32_dpp v87, v87, v87 quad_perm:[1,0,3,2] row_mask:0xf bank_mask:0xf
	v_mul_f32_e32 v134, s29, v62
	v_mul_f32_e32 v135, s35, v62
	v_add_f32_dpp v87, v87, v87 quad_perm:[2,3,0,1] row_mask:0xf bank_mask:0xf
	v_fmac_f32_e32 v135, s33, v63
	v_mul_f32_e32 v92, s31, v62
	v_mov_b32_dpp v90, v87 row_newbcast:0 row_mask:0xf bank_mask:0xf
	v_add_f32_dpp v92, v87, v92 row_newbcast:4 row_mask:0xf bank_mask:0xf
	v_add_f32_dpp v91, v87, v134 row_newbcast:8 row_mask:0xf bank_mask:0xf
	v_pk_fma_f32 v[138:139], v[26:27], v[90:91], v[138:139] op_sel_hi:[1,0,1] neg_lo:[0,1,0] neg_hi:[0,1,0]
	v_fma_f32 v92, -v90, s30, v92
	v_pk_fma_f32 v[140:141], v[28:29], v[90:91], v[140:141] op_sel_hi:[1,0,1] neg_lo:[0,1,0] neg_hi:[0,1,0]
	v_add_f32_dpp v93, v87, v135 row_newbcast:12 row_mask:0xf bank_mask:0xf
	v_pk_fma_f32 v[138:139], v[34:35], v[92:93], v[138:139] op_sel_hi:[1,0,1] neg_lo:[0,1,0] neg_hi:[0,1,0]
	v_pk_fma_f32 v[140:141], v[36:37], v[92:93], v[140:141] op_sel_hi:[1,0,1] neg_lo:[0,1,0] neg_hi:[0,1,0]
	s_waitcnt lgkmcnt(0)
	s_load_dwordx8 s[88:95], s[96:97], 0x1a0
	v_pk_mul_f32 v[82:83], v[138:139], v[6:7]
	v_fma_f32 v91, -v90, s28, v91
	v_pk_mul_f32 v[84:85], v[138:139], v[10:11]
	v_fma_f32 v93, -v90, s34, v93
	v_pk_mul_f32 v[86:87], v[138:139], v[14:15]
	v_fma_f32 v93, -v92, s32, v93
	v_pk_mul_f32 v[88:89], v[138:139], v[18:19]
	ds_write2_b32 v166, v91, v93 offset0:64 offset1:80
	v_pk_fma_f32 v[82:83], v[140:141], v[8:9], v[82:83]
	ds_read_b128 v[22:25], v0 offset:41984
	v_pk_fma_f32 v[84:85], v[140:141], v[12:13], v[84:85]
	ds_read_b128 v[26:29], v0 offset:42240
	v_pk_fma_f32 v[86:87], v[140:141], v[16:17], v[86:87]
	ds_read_b128 v[30:33], v0 offset:42496
	v_pk_fma_f32 v[88:89], v[140:141], v[20:21], v[88:89]
	ds_read_b128 v[34:37], v0 offset:42752
	v_pk_mul_f32 v[138:139], v[138:139], v[42:43]
	ds_read_b128 v[38:41], v0 offset:43008
	v_pk_mul_f32 v[140:141], v[140:141], v[44:45]
	ds_read2st64_b32 v[62:63], v158 offset0:169 offset1:170
	v_add_f32_e32 v82, v82, v83
	v_add_f32_e32 v84, v84, v85
	v_add_f32_e32 v86, v86, v87
	v_add_f32_e32 v88, v88, v89
	ds_read_b128 v[6:9], v0 offset:40960
	ds_read_b128 v[10:13], v0 offset:41216
	ds_read_b128 v[14:17], v0 offset:41472
	ds_read_b128 v[18:21], v0 offset:41728
	v_add_f32_dpp v83, v82, v82 row_mirror row_mask:0xf bank_mask:0xf
	v_add_f32_dpp v83, v84, v84 row_mirror row_mask:0xf bank_mask:0xc
	v_add_f32_dpp v85, v86, v86 row_mirror row_mask:0xf bank_mask:0xf
	v_add_f32_dpp v85, v88, v88 row_mirror row_mask:0xf bank_mask:0xc
	v_add_f32_dpp v87, v83, v83 row_half_mirror row_mask:0xf bank_mask:0xf
	v_pk_fma_f32 v[138:139], v[50:51], v[72:73], v[138:139] op_sel_hi:[1,0,1]
	v_pk_fma_f32 v[140:141], v[52:53], v[72:73], v[140:141] op_sel_hi:[1,0,1]
	v_add_f32_dpp v87, v85, v85 row_half_mirror row_mask:0xf bank_mask:0xa
	v_pk_fma_f32 v[138:139], v[58:59], v[72:73], v[138:139] op_sel:[0,1,0] op_sel_hi:[1,1,1]
	v_pk_fma_f32 v[140:141], v[60:61], v[72:73], v[140:141] op_sel:[0,1,0] op_sel_hi:[1,1,1]
	v_add_f32_dpp v87, v87, v87 quad_perm:[1,0,3,2] row_mask:0xf bank_mask:0xf
	v_mul_f32_e32 v134, s5, v72
	v_mul_f32_e32 v135, s11, v72
	v_add_f32_dpp v87, v87, v87 quad_perm:[2,3,0,1] row_mask:0xf bank_mask:0xf
	v_fmac_f32_e32 v135, s9, v73
	v_mul_f32_e32 v92, s7, v72
	v_mov_b32_dpp v90, v87 row_newbcast:0 row_mask:0xf bank_mask:0xf
	v_add_f32_dpp v92, v87, v92 row_newbcast:4 row_mask:0xf bank_mask:0xf
	v_add_f32_dpp v91, v87, v134 row_newbcast:8 row_mask:0xf bank_mask:0xf
	v_pk_fma_f32 v[138:139], v[46:47], v[90:91], v[138:139] op_sel_hi:[1,0,1] neg_lo:[0,1,0] neg_hi:[0,1,0]
	v_fma_f32 v92, -v90, s6, v92
	v_pk_fma_f32 v[140:141], v[48:49], v[90:91], v[140:141] op_sel_hi:[1,0,1] neg_lo:[0,1,0] neg_hi:[0,1,0]
	v_add_f32_dpp v93, v87, v135 row_newbcast:12 row_mask:0xf bank_mask:0xf
	v_pk_fma_f32 v[138:139], v[54:55], v[92:93], v[138:139] op_sel_hi:[1,0,1] neg_lo:[0,1,0] neg_hi:[0,1,0]
	v_pk_fma_f32 v[140:141], v[56:57], v[92:93], v[140:141] op_sel_hi:[1,0,1] neg_lo:[0,1,0] neg_hi:[0,1,0]
	s_waitcnt lgkmcnt(0)
	s_load_dwordx8 s[28:35], s[96:97], 0x1c0
	v_pk_mul_f32 v[82:83], v[138:139], v[6:7]
	v_fma_f32 v91, -v90, s4, v91
	v_pk_mul_f32 v[84:85], v[138:139], v[10:11]
	v_fma_f32 v93, -v90, s10, v93
	v_pk_mul_f32 v[86:87], v[138:139], v[14:15]
	v_fma_f32 v93, -v92, s8, v93
	v_pk_mul_f32 v[88:89], v[138:139], v[18:19]
	ds_write2_b32 v166, v91, v93 offset0:96 offset1:112
	v_pk_fma_f32 v[82:83], v[140:141], v[8:9], v[82:83]
	ds_read_b128 v[42:45], v0 offset:45056
	v_pk_fma_f32 v[84:85], v[140:141], v[12:13], v[84:85]
	ds_read_b128 v[46:49], v0 offset:45312
	v_pk_fma_f32 v[86:87], v[140:141], v[16:17], v[86:87]
	ds_read_b128 v[50:53], v0 offset:45568
	v_pk_fma_f32 v[88:89], v[140:141], v[20:21], v[88:89]
	ds_read_b128 v[54:57], v0 offset:45824
	v_pk_mul_f32 v[138:139], v[138:139], v[22:23]
	ds_read_b128 v[58:61], v0 offset:46080
	v_pk_mul_f32 v[140:141], v[140:141], v[24:25]
	ds_read2st64_b32 v[72:73], v158 offset0:181 offset1:182
	v_add_f32_e32 v82, v82, v83
	v_add_f32_e32 v84, v84, v85
	v_add_f32_e32 v86, v86, v87
	v_add_f32_e32 v88, v88, v89
	ds_read_b128 v[6:9], v0 offset:44032
	ds_read_b128 v[10:13], v0 offset:44288
	ds_read_b128 v[14:17], v0 offset:44544
	ds_read_b128 v[18:21], v0 offset:44800
	v_add_f32_dpp v83, v82, v82 row_mirror row_mask:0xf bank_mask:0xf
	v_add_f32_dpp v83, v84, v84 row_mirror row_mask:0xf bank_mask:0xc
	v_add_f32_dpp v85, v86, v86 row_mirror row_mask:0xf bank_mask:0xf
	v_add_f32_dpp v85, v88, v88 row_mirror row_mask:0xf bank_mask:0xc
	v_add_f32_dpp v87, v83, v83 row_half_mirror row_mask:0xf bank_mask:0xf
	v_pk_fma_f32 v[138:139], v[30:31], v[62:63], v[138:139] op_sel_hi:[1,0,1]
	v_pk_fma_f32 v[140:141], v[32:33], v[62:63], v[140:141] op_sel_hi:[1,0,1]
	v_add_f32_dpp v87, v85, v85 row_half_mirror row_mask:0xf bank_mask:0xa
	v_pk_fma_f32 v[138:139], v[38:39], v[62:63], v[138:139] op_sel:[0,1,0] op_sel_hi:[1,1,1]
	v_pk_fma_f32 v[140:141], v[40:41], v[62:63], v[140:141] op_sel:[0,1,0] op_sel_hi:[1,1,1]
	v_add_f32_dpp v87, v87, v87 quad_perm:[1,0,3,2] row_mask:0xf bank_mask:0xf
	v_mul_f32_e32 v134, s77, v62
	v_mul_f32_e32 v135, s83, v62
	v_add_f32_dpp v87, v87, v87 quad_perm:[2,3,0,1] row_mask:0xf bank_mask:0xf
	v_fmac_f32_e32 v135, s81, v63
	v_mul_f32_e32 v92, s79, v62
	v_mov_b32_dpp v90, v87 row_newbcast:0 row_mask:0xf bank_mask:0xf
	v_add_f32_dpp v92, v87, v92 row_newbcast:4 row_mask:0xf bank_mask:0xf
	v_add_f32_dpp v91, v87, v134 row_newbcast:8 row_mask:0xf bank_mask:0xf
	v_pk_fma_f32 v[138:139], v[26:27], v[90:91], v[138:139] op_sel_hi:[1,0,1] neg_lo:[0,1,0] neg_hi:[0,1,0]
	v_fma_f32 v92, -v90, s78, v92
	v_pk_fma_f32 v[140:141], v[28:29], v[90:91], v[140:141] op_sel_hi:[1,0,1] neg_lo:[0,1,0] neg_hi:[0,1,0]
	v_add_f32_dpp v93, v87, v135 row_newbcast:12 row_mask:0xf bank_mask:0xf
	v_pk_fma_f32 v[138:139], v[34:35], v[92:93], v[138:139] op_sel_hi:[1,0,1] neg_lo:[0,1,0] neg_hi:[0,1,0]
	v_pk_fma_f32 v[140:141], v[36:37], v[92:93], v[140:141] op_sel_hi:[1,0,1] neg_lo:[0,1,0] neg_hi:[0,1,0]
	s_waitcnt lgkmcnt(0)
	s_load_dwordx8 s[4:11], s[96:97], 0x1e0
	v_pk_mul_f32 v[82:83], v[138:139], v[6:7]
	v_fma_f32 v91, -v90, s76, v91
	v_pk_mul_f32 v[84:85], v[138:139], v[10:11]
	v_fma_f32 v93, -v90, s82, v93
	v_pk_mul_f32 v[86:87], v[138:139], v[14:15]
	v_fma_f32 v93, -v92, s80, v93
	v_pk_mul_f32 v[88:89], v[138:139], v[18:19]
	ds_write2_b32 v166, v91, v93 offset0:128 offset1:144
	v_pk_fma_f32 v[82:83], v[140:141], v[8:9], v[82:83]
	ds_read_b128 v[22:25], v0 offset:48128
	v_pk_fma_f32 v[84:85], v[140:141], v[12:13], v[84:85]
	ds_read_b128 v[26:29], v0 offset:48384
	v_pk_fma_f32 v[86:87], v[140:141], v[16:17], v[86:87]
	ds_read_b128 v[30:33], v0 offset:48640
	v_pk_fma_f32 v[88:89], v[140:141], v[20:21], v[88:89]
	ds_read_b128 v[34:37], v0 offset:48896
	v_pk_mul_f32 v[138:139], v[138:139], v[42:43]
	ds_read_b128 v[38:41], v0 offset:49152
	v_pk_mul_f32 v[140:141], v[140:141], v[44:45]
	ds_read2st64_b32 v[62:63], v158 offset0:193 offset1:194
	v_add_f32_e32 v82, v82, v83
	v_add_f32_e32 v84, v84, v85
	v_add_f32_e32 v86, v86, v87
	v_add_f32_e32 v88, v88, v89
	ds_read_b128 v[6:9], v0 offset:47104
	ds_read_b128 v[10:13], v0 offset:47360
	ds_read_b128 v[14:17], v0 offset:47616
	ds_read_b128 v[18:21], v0 offset:47872
	v_add_f32_dpp v83, v82, v82 row_mirror row_mask:0xf bank_mask:0xf
	v_add_f32_dpp v83, v84, v84 row_mirror row_mask:0xf bank_mask:0xc
	v_add_f32_dpp v85, v86, v86 row_mirror row_mask:0xf bank_mask:0xf
	v_add_f32_dpp v85, v88, v88 row_mirror row_mask:0xf bank_mask:0xc
	v_add_f32_dpp v87, v83, v83 row_half_mirror row_mask:0xf bank_mask:0xf
	v_pk_fma_f32 v[138:139], v[50:51], v[72:73], v[138:139] op_sel_hi:[1,0,1]
	v_pk_fma_f32 v[140:141], v[52:53], v[72:73], v[140:141] op_sel_hi:[1,0,1]
	v_add_f32_dpp v87, v85, v85 row_half_mirror row_mask:0xf bank_mask:0xa
	v_pk_fma_f32 v[138:139], v[58:59], v[72:73], v[138:139] op_sel:[0,1,0] op_sel_hi:[1,1,1]
	v_pk_fma_f32 v[140:141], v[60:61], v[72:73], v[140:141] op_sel:[0,1,0] op_sel_hi:[1,1,1]
	v_add_f32_dpp v87, v87, v87 quad_perm:[1,0,3,2] row_mask:0xf bank_mask:0xf
	v_mul_f32_e32 v134, s89, v72
	v_mul_f32_e32 v135, s95, v72
	v_add_f32_dpp v87, v87, v87 quad_perm:[2,3,0,1] row_mask:0xf bank_mask:0xf
	v_fmac_f32_e32 v135, s93, v73
	v_mul_f32_e32 v92, s91, v72
	v_mov_b32_dpp v90, v87 row_newbcast:0 row_mask:0xf bank_mask:0xf
	v_add_f32_dpp v92, v87, v92 row_newbcast:4 row_mask:0xf bank_mask:0xf
	v_add_f32_dpp v91, v87, v134 row_newbcast:8 row_mask:0xf bank_mask:0xf
	v_pk_fma_f32 v[138:139], v[46:47], v[90:91], v[138:139] op_sel_hi:[1,0,1] neg_lo:[0,1,0] neg_hi:[0,1,0]
	v_fma_f32 v92, -v90, s90, v92
	v_pk_fma_f32 v[140:141], v[48:49], v[90:91], v[140:141] op_sel_hi:[1,0,1] neg_lo:[0,1,0] neg_hi:[0,1,0]
	v_add_f32_dpp v93, v87, v135 row_newbcast:12 row_mask:0xf bank_mask:0xf
	v_pk_fma_f32 v[138:139], v[54:55], v[92:93], v[138:139] op_sel_hi:[1,0,1] neg_lo:[0,1,0] neg_hi:[0,1,0]
	v_pk_fma_f32 v[140:141], v[56:57], v[92:93], v[140:141] op_sel_hi:[1,0,1] neg_lo:[0,1,0] neg_hi:[0,1,0]
	s_waitcnt lgkmcnt(0)
	s_load_dwordx8 s[76:83], s[96:97], 0x200
	v_pk_mul_f32 v[82:83], v[138:139], v[6:7]
	v_fma_f32 v91, -v90, s88, v91
	v_pk_mul_f32 v[84:85], v[138:139], v[10:11]
	v_fma_f32 v93, -v90, s94, v93
	v_pk_mul_f32 v[86:87], v[138:139], v[14:15]
	v_fma_f32 v93, -v92, s92, v93
	v_pk_mul_f32 v[88:89], v[138:139], v[18:19]
	ds_write2_b32 v166, v91, v93 offset0:160 offset1:176
	v_pk_fma_f32 v[82:83], v[140:141], v[8:9], v[82:83]
	ds_read_b128 v[42:45], v0 offset:51200
	v_pk_fma_f32 v[84:85], v[140:141], v[12:13], v[84:85]
	ds_read_b128 v[46:49], v0 offset:51456
	v_pk_fma_f32 v[86:87], v[140:141], v[16:17], v[86:87]
	ds_read_b128 v[50:53], v0 offset:51712
	v_pk_fma_f32 v[88:89], v[140:141], v[20:21], v[88:89]
	ds_read_b128 v[54:57], v0 offset:51968
	v_pk_mul_f32 v[138:139], v[138:139], v[22:23]
	ds_read_b128 v[58:61], v0 offset:52224
	v_pk_mul_f32 v[140:141], v[140:141], v[24:25]
	ds_read2st64_b32 v[72:73], v158 offset0:205 offset1:206
	v_add_f32_e32 v82, v82, v83
	v_add_f32_e32 v84, v84, v85
	v_add_f32_e32 v86, v86, v87
	v_add_f32_e32 v88, v88, v89
	ds_read_b128 v[6:9], v0 offset:50176
	ds_read_b128 v[10:13], v0 offset:50432
	ds_read_b128 v[14:17], v0 offset:50688
	ds_read_b128 v[18:21], v0 offset:50944
	v_add_f32_dpp v83, v82, v82 row_mirror row_mask:0xf bank_mask:0xf
	v_add_f32_dpp v83, v84, v84 row_mirror row_mask:0xf bank_mask:0xc
	v_add_f32_dpp v85, v86, v86 row_mirror row_mask:0xf bank_mask:0xf
	v_add_f32_dpp v85, v88, v88 row_mirror row_mask:0xf bank_mask:0xc
	v_add_f32_dpp v87, v83, v83 row_half_mirror row_mask:0xf bank_mask:0xf
	v_pk_fma_f32 v[138:139], v[30:31], v[62:63], v[138:139] op_sel_hi:[1,0,1]
	v_pk_fma_f32 v[140:141], v[32:33], v[62:63], v[140:141] op_sel_hi:[1,0,1]
	v_add_f32_dpp v87, v85, v85 row_half_mirror row_mask:0xf bank_mask:0xa
	v_pk_fma_f32 v[138:139], v[38:39], v[62:63], v[138:139] op_sel:[0,1,0] op_sel_hi:[1,1,1]
	v_pk_fma_f32 v[140:141], v[40:41], v[62:63], v[140:141] op_sel:[0,1,0] op_sel_hi:[1,1,1]
	v_add_f32_dpp v87, v87, v87 quad_perm:[1,0,3,2] row_mask:0xf bank_mask:0xf
	v_mul_f32_e32 v134, s29, v62
	v_mul_f32_e32 v135, s35, v62
	v_add_f32_dpp v87, v87, v87 quad_perm:[2,3,0,1] row_mask:0xf bank_mask:0xf
	v_fmac_f32_e32 v135, s33, v63
	v_mul_f32_e32 v92, s31, v62
	v_mov_b32_dpp v90, v87 row_newbcast:0 row_mask:0xf bank_mask:0xf
	v_add_f32_dpp v92, v87, v92 row_newbcast:4 row_mask:0xf bank_mask:0xf
	v_add_f32_dpp v91, v87, v134 row_newbcast:8 row_mask:0xf bank_mask:0xf
	v_pk_fma_f32 v[138:139], v[26:27], v[90:91], v[138:139] op_sel_hi:[1,0,1] neg_lo:[0,1,0] neg_hi:[0,1,0]
	v_fma_f32 v92, -v90, s30, v92
	v_pk_fma_f32 v[140:141], v[28:29], v[90:91], v[140:141] op_sel_hi:[1,0,1] neg_lo:[0,1,0] neg_hi:[0,1,0]
	v_add_f32_dpp v93, v87, v135 row_newbcast:12 row_mask:0xf bank_mask:0xf
	v_pk_fma_f32 v[138:139], v[34:35], v[92:93], v[138:139] op_sel_hi:[1,0,1] neg_lo:[0,1,0] neg_hi:[0,1,0]
	v_pk_fma_f32 v[140:141], v[36:37], v[92:93], v[140:141] op_sel_hi:[1,0,1] neg_lo:[0,1,0] neg_hi:[0,1,0]
	s_waitcnt lgkmcnt(0)
	s_load_dwordx8 s[88:95], s[96:97], 0x220
	v_pk_mul_f32 v[82:83], v[138:139], v[6:7]
	v_fma_f32 v91, -v90, s28, v91
	v_pk_mul_f32 v[84:85], v[138:139], v[10:11]
	v_fma_f32 v93, -v90, s34, v93
	v_pk_mul_f32 v[86:87], v[138:139], v[14:15]
	v_fma_f32 v93, -v92, s32, v93
	v_pk_mul_f32 v[88:89], v[138:139], v[18:19]
	ds_write2_b32 v166, v91, v93 offset0:192 offset1:208
	v_pk_fma_f32 v[82:83], v[140:141], v[8:9], v[82:83]
	v_pk_fma_f32 v[84:85], v[140:141], v[12:13], v[84:85]
	v_pk_fma_f32 v[86:87], v[140:141], v[16:17], v[86:87]
	v_pk_fma_f32 v[88:89], v[140:141], v[20:21], v[88:89]
	v_pk_mul_f32 v[138:139], v[138:139], v[42:43]
	v_pk_mul_f32 v[140:141], v[140:141], v[44:45]
	v_add_f32_e32 v82, v82, v83
	v_add_f32_e32 v84, v84, v85
	v_add_f32_e32 v86, v86, v87
	v_add_f32_e32 v88, v88, v89
	v_add_f32_dpp v83, v82, v82 row_mirror row_mask:0xf bank_mask:0xf
	v_add_f32_dpp v83, v84, v84 row_mirror row_mask:0xf bank_mask:0xc
	v_add_f32_dpp v85, v86, v86 row_mirror row_mask:0xf bank_mask:0xf
	v_add_f32_dpp v85, v88, v88 row_mirror row_mask:0xf bank_mask:0xc
	v_add_f32_dpp v87, v83, v83 row_half_mirror row_mask:0xf bank_mask:0xf
	v_pk_fma_f32 v[138:139], v[50:51], v[72:73], v[138:139] op_sel_hi:[1,0,1]
	v_pk_fma_f32 v[140:141], v[52:53], v[72:73], v[140:141] op_sel_hi:[1,0,1]
	v_add_f32_dpp v87, v85, v85 row_half_mirror row_mask:0xf bank_mask:0xa
	v_pk_fma_f32 v[138:139], v[58:59], v[72:73], v[138:139] op_sel:[0,1,0] op_sel_hi:[1,1,1]
	v_pk_fma_f32 v[140:141], v[60:61], v[72:73], v[140:141] op_sel:[0,1,0] op_sel_hi:[1,1,1]
	v_add_f32_dpp v87, v87, v87 quad_perm:[1,0,3,2] row_mask:0xf bank_mask:0xf
	v_mul_f32_e32 v134, s5, v72
	v_mul_f32_e32 v135, s11, v72
	v_add_f32_dpp v87, v87, v87 quad_perm:[2,3,0,1] row_mask:0xf bank_mask:0xf
	v_fmac_f32_e32 v135, s9, v73
	v_mul_f32_e32 v92, s7, v72
	v_mov_b32_dpp v90, v87 row_newbcast:0 row_mask:0xf bank_mask:0xf
	v_add_f32_dpp v92, v87, v92 row_newbcast:4 row_mask:0xf bank_mask:0xf
	v_add_f32_dpp v91, v87, v134 row_newbcast:8 row_mask:0xf bank_mask:0xf
	v_pk_fma_f32 v[138:139], v[46:47], v[90:91], v[138:139] op_sel_hi:[1,0,1] neg_lo:[0,1,0] neg_hi:[0,1,0]
	v_fma_f32 v92, -v90, s6, v92
	v_pk_fma_f32 v[140:141], v[48:49], v[90:91], v[140:141] op_sel_hi:[1,0,1] neg_lo:[0,1,0] neg_hi:[0,1,0]
	v_add_f32_dpp v93, v87, v135 row_newbcast:12 row_mask:0xf bank_mask:0xf
	v_pk_fma_f32 v[138:139], v[54:55], v[92:93], v[138:139] op_sel_hi:[1,0,1] neg_lo:[0,1,0] neg_hi:[0,1,0]
	v_pk_fma_f32 v[140:141], v[56:57], v[92:93], v[140:141] op_sel_hi:[1,0,1] neg_lo:[0,1,0] neg_hi:[0,1,0]
	v_fma_f32 v91, -v90, s4, v91
	v_fma_f32 v93, -v90, s10, v93
	v_fma_f32 v93, -v92, s8, v93
	ds_write2_b32 v166, v91, v93 offset0:224 offset1:240

.LBB0_865:
	v_readlane_b32 s4, v255, 0
	v_readlane_b32 s5, v255, 1
	v_readlane_b32 s6, v255, 2
	v_readlane_b32 s7, v255, 3
	v_readlane_b32 s8, v255, 4
	v_readlane_b32 s9, v255, 5
	v_readlane_b32 s10, v255, 6
	v_readlane_b32 s11, v255, 7
	v_readlane_b32 s28, v255, 8
	v_readlane_b32 s29, v255, 9
	v_readlane_b32 s30, v255, 10
	v_readlane_b32 s31, v255, 11
	v_readlane_b32 s32, v255, 12
	v_readlane_b32 s33, v255, 13
	v_readlane_b32 s34, v255, 14
	v_readlane_b32 s35, v255, 15
	v_readlane_b32 s76, v255, 16
	v_readlane_b32 s77, v255, 17
	v_readlane_b32 s78, v255, 18
	v_readlane_b32 s79, v255, 19
	v_readlane_b32 s80, v255, 20
	v_readlane_b32 s81, v255, 21
	v_readlane_b32 s82, v255, 22
	v_readlane_b32 s83, v255, 23
	v_readlane_b32 s88, v255, 24
	v_readlane_b32 s89, v255, 25
	v_readlane_b32 s90, v255, 26
	v_readlane_b32 s91, v255, 27
	v_readlane_b32 s92, v255, 28
	v_readlane_b32 s93, v255, 29
	v_readlane_b32 s94, v255, 30
	v_readlane_b32 s95, v255, 31
	v_readlane_b32 s96, v255, 32
	v_readlane_b32 s97, v255, 33
	s_nop 4
	s_and_saveexec_b64 s[24:25], s[42:43]
	s_cbranch_execz .LBB0_867
	s_waitcnt vmcnt(0)
	ds_read_b64 v[2:3], v157 offset:2048
	v_lshlrev_b32_e32 v0, 1, v120
	s_waitcnt lgkmcnt(0)
	v_cvt_pk_bf16_f32 v4, v2, v3
	v_lshl_add_u64 v[2:3], s[0:1], 0, v[0:1]
	v_lshlrev_b32_e32 v0, 1, v118
	v_lshl_add_u64 v[2:3], v[2:3], 0, v[0:1]
	v_add_co_u32_e32 v2, vcc, 0x3fe0000, v2
	s_nop 1
	v_addc_co_u32_e32 v3, vcc, 0, v3, vcc
	global_store_dword v[2:3], v4, off

	.amdhsa_kernel _Z8fwd_mega6Params
		.amdhsa_group_segment_fixed_size 0
		.amdhsa_private_segment_fixed_size 0
		.amdhsa_kernarg_size 552
		.amdhsa_user_sgpr_count 2
		.amdhsa_user_sgpr_dispatch_ptr 0
		.amdhsa_user_sgpr_queue_ptr 0
		.amdhsa_user_sgpr_kernarg_segment_ptr 1
		.amdhsa_user_sgpr_dispatch_id 0
		.amdhsa_user_sgpr_kernarg_preload_length 0
		.amdhsa_user_sgpr_kernarg_preload_offset 0
		.amdhsa_user_sgpr_private_segment_size 0
		.amdhsa_uses_dynamic_stack 0
		.amdhsa_enable_private_segment 0
		.amdhsa_system_sgpr_workgroup_id_x 1
		.amdhsa_system_sgpr_workgroup_id_y 0
		.amdhsa_system_sgpr_workgroup_id_z 0
		.amdhsa_system_sgpr_workgroup_info 0
		.amdhsa_system_vgpr_workitem_id 2
		.amdhsa_next_free_vgpr 256
		.amdhsa_next_free_sgpr 102
		.amdhsa_accum_offset 256
		.amdhsa_reserve_vcc 1
		.amdhsa_float_round_mode_32 0
		.amdhsa_float_round_mode_16_64 0
		.amdhsa_float_denorm_mode_32 3
		.amdhsa_float_denorm_mode_16_64 3
		.amdhsa_dx10_clamp 1
		.amdhsa_ieee_mode 1
		.amdhsa_fp16_overflow 0
		.amdhsa_tg_split 0
		.amdhsa_exception_fp_ieee_invalid_op 0
		.amdhsa_exception_fp_denorm_src 0
		.amdhsa_exception_fp_ieee_div_zero 0
		.amdhsa_exception_fp_ieee_overflow 0
		.amdhsa_exception_fp_ieee_underflow 0
		.amdhsa_exception_fp_ieee_inexact 0
		.amdhsa_exception_int_div_zero 0
	.end_amdhsa_kernel

amdhsa.kernels:
  - .agpr_count:     0
    .args:
      - .offset:         0
        .size:           296
        .value_kind:     by_value
      - .offset:         296
        .size:           4
        .value_kind:     hidden_block_count_x
      - .offset:         300
        .size:           4
        .value_kind:     hidden_block_count_y
      - .offset:         304
        .size:           4
        .value_kind:     hidden_block_count_z
      - .offset:         308
        .size:           2
        .value_kind:     hidden_group_size_x
      - .offset:         310
        .size:           2
        .value_kind:     hidden_group_size_y
      - .offset:         312
        .size:           2
        .value_kind:     hidden_group_size_z
      - .offset:         314
        .size:           2
        .value_kind:     hidden_remainder_x
      - .offset:         316
        .size:           2
        .value_kind:     hidden_remainder_y
      - .offset:         318
        .size:           2
        .value_kind:     hidden_remainder_z
      - .offset:         336
        .size:           8
        .value_kind:     hidden_global_offset_x
      - .offset:         344
        .size:           8
        .value_kind:     hidden_global_offset_y
      - .offset:         352
        .size:           8
        .value_kind:     hidden_global_offset_z
      - .offset:         360
        .size:           2
        .value_kind:     hidden_grid_dims
      - .offset:         384
        .size:           8
        .value_kind:     hidden_multigrid_sync_arg
      - .offset:         416
        .size:           4
        .value_kind:     hidden_dynamic_lds_size
    .group_segment_fixed_size: 0
    .kernarg_segment_align: 8
    .kernarg_segment_size: 552
    .language:       OpenCL C
    .language_version:
      - 2
      - 0
    .max_flat_workgroup_size: 512
    .name:           _Z8fwd_mega6Params
    .private_segment_fixed_size: 0
    .sgpr_count:     108
    .sgpr_spill_count: 282
    .symbol:         _Z8fwd_mega6Params.kd
    .uniform_work_group_size: 1
    .uses_dynamic_stack: false
    .vgpr_count:     256
    .vgpr_spill_count: 0
    .wavefront_size: 64
